# lean12 = lean11 + dead denormal-range fixup around rsqrt(mean+1e-6) removed at 20 sites (condition can never be true)
# speedup vs baseline: 1.0040x; 1.0040x over previous
; __device__ __forceinline__ void unpack8(const v4u r, float* x) { x[0] = bflo(r.x); x[1] = bfhi(r.x); x[2] = bflo(r.y); x[3] = bfhi(r.y); x[4] = bflo(r.z); x[5] = bfhi(r.z); x[6] = bflo(r.w); x[7] = bfhi(r.w); }
; __device__ __forceinline__ v4u pack8(const float* x) { v4u o; o.x = pk2(x[0], x[1]); o.y = pk2(x[2], x[3]); o.z = pk2(x[4], x[5]); o.w = pk2(x[6], x[7]); return o; }
; __device__ __forceinline__ float sigmoidf_(float x) { return __builtin_amdgcn_rcpf(1.0f + __builtin_amdgcn_exp2f(-1.4426950408889634f * x)); }
; __device__ __forceinline__ size_t tl(int row, int col, int K) { return (size_t)(row >> 8) * ((size_t)256 * K) + (size_t)(col >> 6) * (256 * 64) + (size_t)((row & 255) * 64 + (col & 63)); }
; __device__ __forceinline__ void m3_compute(const M3In& I, const float* mnorm, u16* YB, LAS unsigned char* lds, int un, int tid) {
;     ...
;     {
;         const int t = s; const float di = dinv[t]; float hv[8]; float sm = 0.f;
; #pragma unroll
;         for (int i = 0; i < 8; ++i) { hv[i] = NUM[t * 65 + dg * 8 + i] * di; sm += hv[i]; }
;         sm = red8(sm);
;         const float mu = sm * (1.0f / 64.0f); float vs = 0.f;
; #pragma unroll
;         for (int i = 0; i < 8; ++i) { hv[i] -= mu; vs += hv[i] * hv[i]; }
;         vs = red8(vs);
;         const float rstd = rsqrtf(vs * (1.0f / 64.0f) + EPS);
;         float og[8]; unpack8(I.mo, og);
;         float o[8];
; #pragma unroll
;         for (int i = 0; i < 8; ++i) o[i] = hv[i] * rstd * mnorm[h * 64 + dg * 8 + i] * sigmoidf_(og[i]);
;         *(v4u*)(YB + tl(r0 + t, h * 64 + dg * 8, 256)) = pack8(o); }
.LBB0_957:
	s_or_b64 exec, exec, s[76:77]
	v_lshlrev_b32_e32 v48, 16, v4
	v_and_b32_e32 v53, 0xffff0000, v4
	v_mul_f32_e32 v4, 0xbfb8aa3b, v48
	v_exp_f32_e32 v4, v4
	s_lshl_b64 s[22:23], s[70:71], 2
	s_add_u32 s22, s51, s22
	s_addc_u32 s23, s40, s23
	s_waitcnt lgkmcnt(0)
	s_barrier
	v_lshlrev_b32_e32 v48, 2, v140
	ds_read_b32 v52, v136 offset:1280
	v_lshlrev_b32_e32 v54, 16, v5
	v_and_b32_e32 v56, 0xffff0000, v5
	v_lshlrev_b32_e32 v57, 16, v6
	v_and_b32_e32 v58, 0xffff0000, v6
	v_lshlrev_b32_e32 v59, 16, v7
	v_and_b32_e32 v60, 0xffff0000, v7
	v_add_f32_e32 v55, 1.0, v4
	global_load_dwordx4 v[4:7], v48, s[22:23] offset:16
	s_nop 0
	global_load_dwordx4 v[48:51], v48, s[22:23]
	v_mul_f32_e32 v53, 0xbfb8aa3b, v53
	v_exp_f32_e32 v53, v53
	v_mul_f32_e32 v54, 0xbfb8aa3b, v54
	v_exp_f32_e32 v61, v54
	v_mul_f32_e32 v56, 0xbfb8aa3b, v56
	v_add_f32_e32 v53, 1.0, v53
	v_rcp_f32_e32 v54, v55
	v_rcp_f32_e32 v55, v53
	v_add_f32_e32 v53, 1.0, v61
	v_exp_f32_e32 v61, v56
	v_mul_f32_e32 v56, 0xbfb8aa3b, v57
	v_exp_f32_e32 v62, v56
	v_mul_f32_e32 v58, 0xbfb8aa3b, v58
	v_rcp_f32_e32 v56, v53
	v_add_f32_e32 v53, 1.0, v61
	v_exp_f32_e32 v61, v58
	v_mul_f32_e32 v58, 0xbfb8aa3b, v59
	v_rcp_f32_e32 v57, v53
	v_add_f32_e32 v53, 1.0, v62
	v_exp_f32_e32 v62, v58
	v_rcp_f32_e32 v58, v53
	v_add_f32_e32 v53, 1.0, v61
	v_rcp_f32_e32 v59, v53
	v_add_f32_e32 v76, 1.0, v62
	v_mul_f32_e32 v53, 0xbfb8aa3b, v60
	v_add_u32_e32 v60, 0xbc18, v110
	v_add_u32_e32 v62, 0xbc10, v110
	v_add_u32_e32 v64, 0xbc08, v110
	v_add_u32_e32 v66, 0xbc00, v110
	ds_read2_b32 v[60:61], v60 offset1:1
	ds_read2_b32 v[62:63], v62 offset1:1
	ds_read2_b32 v[64:65], v64 offset1:1
	ds_read2_b32 v[66:67], v66 offset1:1
	v_exp_f32_e32 v77, v53
	s_waitcnt lgkmcnt(3)
	v_pk_mul_f32 v[68:69], v[52:53], v[60:61] op_sel_hi:[0,1]
	s_waitcnt lgkmcnt(2)
	v_pk_mul_f32 v[70:71], v[52:53], v[62:63] op_sel_hi:[0,1]
	s_waitcnt lgkmcnt(1)
	v_pk_mul_f32 v[72:73], v[52:53], v[64:65] op_sel_hi:[0,1]
	s_waitcnt lgkmcnt(0)
	v_pk_mul_f32 v[74:75], v[52:53], v[66:67] op_sel_hi:[0,1]
	v_add_f32_e32 v53, 0, v74
	v_add_f32_e32 v53, v53, v75
	v_add_f32_e32 v53, v53, v72
	v_add_f32_e32 v53, v53, v73
	v_add_f32_e32 v53, v53, v70
	v_add_f32_e32 v53, v53, v71
	v_add_f32_e32 v53, v53, v68
	v_add_f32_e32 v53, v53, v69
	s_and_b32 s22, s33, 0xfffff000
	s_or_b32 s22, s22, s50
	v_add_f32_dpp v53, v53, v53 quad_perm:[1,0,3,2] row_mask:0xf bank_mask:0xf bound_ctrl:1
	s_waitcnt vmcnt(11)
	v_mov_b64_e32 v[82:83], v[26:27]
	v_mov_b64_e32 v[86:87], v[22:23]
	v_add_f32_dpp v53, v53, v53 quad_perm:[2,3,0,1] row_mask:0xf bank_mask:0xf bound_ctrl:1
	s_add_i32 s37, s37, s39
	s_add_i32 s33, s33, s41
	v_add_f32_dpp v53, v53, v53 row_half_mirror row_mask:0xf bank_mask:0xf bound_ctrl:1
	v_mul_f32_e32 v68, 0x3c800000, v53
	v_pk_fma_f32 v[66:67], v[52:53], v[66:67], v[68:69] op_sel_hi:[0,1,0] neg_lo:[0,0,1] neg_hi:[0,0,1]
	v_pk_mul_f32 v[70:71], v[66:67], v[66:67]
	v_pk_fma_f32 v[64:65], v[52:53], v[64:65], v[68:69] op_sel_hi:[0,1,0] neg_lo:[0,0,1] neg_hi:[0,0,1]
	v_pk_mul_f32 v[72:73], v[64:65], v[64:65]
	v_pk_fma_f32 v[62:63], v[52:53], v[62:63], v[68:69] op_sel_hi:[0,1,0] neg_lo:[0,0,1] neg_hi:[0,0,1]
	v_pk_fma_f32 v[52:53], v[52:53], v[60:61], v[68:69] op_sel_hi:[0,1,0] neg_lo:[0,0,1] neg_hi:[0,0,1]
	v_add_f32_e32 v68, v70, v71
	v_add_f32_e32 v68, v72, v68
	v_pk_mul_f32 v[74:75], v[62:63], v[62:63]
	v_add_f32_e32 v68, v73, v68
	v_add_f32_e32 v68, v74, v68
	v_pk_mul_f32 v[60:61], v[52:53], v[52:53]
	v_add_f32_e32 v68, v75, v68
	v_add_f32_e32 v60, v60, v68
	v_add_f32_e32 v60, v61, v60
	s_waitcnt vmcnt(9)
	v_mov_b64_e32 v[74:75], v[34:35]
	s_waitcnt vmcnt(2)
	v_mov_b32_e32 v89, v139
	v_add_f32_dpp v60, v60, v60 quad_perm:[1,0,3,2] row_mask:0xf bank_mask:0xf bound_ctrl:1
	v_mov_b32_e32 v88, v138
	v_mov_b32_e32 v91, v137
	v_add_f32_dpp v60, v60, v60 quad_perm:[2,3,0,1] row_mask:0xf bank_mask:0xf bound_ctrl:1
	v_mov_b32_e32 v90, v113
	v_mov_b64_e32 v[72:73], v[32:33]
	v_add_f32_dpp v60, v60, v60 row_half_mirror row_mask:0xf bank_mask:0xf bound_ctrl:1
	v_fmamk_f32 v60, v60, 0x3c800000, v235
	v_mov_b64_e32 v[80:81], v[24:25]
	v_mov_b64_e32 v[84:85], v[20:21]
	v_rsq_f32_e32 v68, v60
	v_add_f32_e32 v61, 1.0, v77
	v_rcp_f32_e32 v60, v76
	v_rcp_f32_e32 v61, v61
	s_nop 0
	v_pk_mul_f32 v[66:67], v[66:67], v[68:69] op_sel_hi:[1,0]
	v_mov_b64_e32 v[78:79], v[30:31]
	s_waitcnt vmcnt(0)
	v_pk_mul_f32 v[48:49], v[48:49], v[66:67]
	s_andn2_b64 vcc, exec, s[74:75]
	v_pk_mul_f32 v[48:49], v[54:55], v[48:49]
	v_pk_mul_f32 v[54:55], v[64:65], v[68:69] op_sel_hi:[1,0]
	v_mov_b64_e32 v[66:67], v[10:11]
	v_pk_mul_f32 v[50:51], v[50:51], v[54:55]
	v_pk_mul_f32 v[54:55], v[62:63], v[68:69] op_sel_hi:[1,0]
	v_pk_mul_f32 v[50:51], v[56:57], v[50:51]
	v_pk_mul_f32 v[4:5], v[4:5], v[54:55]
	v_mov_b64_e32 v[76:77], v[28:29]
	v_pk_mul_f32 v[54:55], v[58:59], v[4:5]
	v_pk_mul_f32 v[4:5], v[52:53], v[68:69] op_sel_hi:[1,0]
	v_mov_b64_e32 v[58:59], v[18:19]
	v_pk_mul_f32 v[4:5], v[6:7], v[4:5]
	v_cvt_pk_bf16_f32 v6, v54, v55
	v_pk_mul_f32 v[52:53], v[60:61], v[4:5]
	v_cvt_pk_bf16_f32 v5, v50, v51
	v_add_u32_e32 v50, s22, v109
	v_cvt_pk_bf16_f32 v4, v48, v49
	v_ashrrev_i32_e32 v48, 8, v50
	v_lshlrev_b32_e32 v50, 6, v50
	v_ashrrev_i32_e32 v49, 31, v48
	s_lshl_b32 s22, s30, 8
	v_and_b32_e32 v50, 0x3fc0, v50
	v_or3_b32 v50, v50, s22, v119
	v_lshlrev_b64 v[48:49], 17, v[48:49]
	v_lshl_add_u64 v[48:49], s[72:73], 0, v[48:49]
	v_lshlrev_b32_e32 v220, 1, v50
	v_cvt_pk_bf16_f32 v7, v52, v53
	v_lshl_add_u64 v[48:49], v[48:49], 0, v[220:221]
	global_store_dwordx4 v[48:49], v[4:7], off
	s_waitcnt lgkmcnt(0)
	s_barrier
	v_mov_b64_e32 v[54:55], v[46:47]
	v_mov_b64_e32 v[4:5], v[40:41]
	v_mov_b64_e32 v[50:51], v[38:39]
	v_mov_b64_e32 v[62:63], v[14:15]
	v_mov_b64_e32 v[70:71], v[2:3]
	s_mov_b32 s22, s42
	v_mov_b64_e32 v[6:7], v[42:43]
	v_mov_b64_e32 v[52:53], v[44:45]
	v_mov_b64_e32 v[48:49], v[36:37]
	v_mov_b64_e32 v[56:57], v[16:17]
	v_mov_b64_e32 v[60:61], v[12:13]
	v_mov_b64_e32 v[64:65], v[8:9]
	v_mov_b64_e32 v[68:69], v[0:1]
	s_cbranch_vccz .LBB0_978

; __device__ __forceinline__ void attn_post(const u16* O, u16* YC, const float* dlam, const float* dnorm, float lambda_init, int gt, int nthreads, int lane) {
;     ...
;     for (int item0 = gt >> 4; item0 < MH * 4; item0 += 8 * stride) {
;         v4u ra[8], rb[8];
; #pragma unroll
;         for (int q = 0; q < 8; ++q) { const int item = item0 + q * stride < MH * 4 ? item0 + q * stride : item0; const int row = item >> 2, hh = item & 3;
;             ra[q] = *(const v4u*)(O + (size_t)row * 1024 + (2 * hh) * 128 + sub * 8); rb[q] = *(const v4u*)(O + (size_t)row * 1024 + (2 * hh + 1) * 128 + sub * 8); }
; #pragma unroll
.LBB0_982:
	v_ashrrev_i32_e32 v0, 2, v62
	v_ashrrev_i32_e32 v1, 31, v0
	v_lshlrev_b64 v[0:1], 11, v[0:1]
	v_and_b32_e32 v2, 0x300, v73
	v_lshl_add_u64 v[0:1], s[16:17], 0, v[0:1]
	v_lshlrev_b32_e32 v220, 1, v2
	v_lshl_add_u64 v[0:1], v[0:1], 0, v[220:221]
	v_lshlrev_b32_e32 v220, 1, v48
	v_lshl_add_u64 v[0:1], v[0:1], 0, v[220:221]
	v_mov_b64_e32 v[64:65], v[146:147]
	v_mov_b64_e32 v[66:67], v[148:149]
	v_mov_b64_e32 v[82:83], v[150:151]
	v_mov_b64_e32 v[84:85], v[152:153]
	v_add_u32_e32 v74, s22, v62
	v_cmp_gt_i32_e64 s[0:1], s81, v74
	v_mov_b32_e32 v3, v221
	v_add_u32_e32 v81, s30, v62
	v_cndmask_b32_e64 v2, v62, v74, s[0:1]
	v_ashrrev_i32_e32 v0, 2, v2
	v_ashrrev_i32_e32 v1, 31, v0
	v_lshlrev_b64 v[0:1], 11, v[0:1]
	v_lshlrev_b32_e32 v2, 9, v2
	v_lshl_add_u64 v[0:1], s[16:17], 0, v[0:1]
	v_and_b32_e32 v2, 0x600, v2
	v_lshl_add_u64 v[0:1], v[0:1], 0, v[2:3]
	v_cmp_gt_i32_e64 s[10:11], s81, v81
	v_lshl_add_u64 v[0:1], v[0:1], 0, v[220:221]
	v_mov_b64_e32 v[86:87], v[154:155]
	v_mov_b64_e32 v[88:89], v[156:157]
	v_mov_b64_e32 v[90:91], v[158:159]
	v_mov_b64_e32 v[92:93], v[160:161]
	v_cndmask_b32_e64 v2, v62, v81, s[10:11]
	v_ashrrev_i32_e32 v0, 2, v2
	v_ashrrev_i32_e32 v1, 31, v0
	v_lshlrev_b64 v[0:1], 11, v[0:1]
	v_lshlrev_b32_e32 v2, 9, v2
	s_mul_i32 s2, s60, 0x60
	v_lshl_add_u64 v[0:1], s[16:17], 0, v[0:1]
	v_and_b32_e32 v2, 0x600, v2
	v_add_u32_e32 v80, s2, v62
	v_lshl_add_u64 v[0:1], v[0:1], 0, v[2:3]
	v_cmp_gt_i32_e64 s[8:9], s81, v80
	v_lshl_add_u64 v[0:1], v[0:1], 0, v[220:221]
	v_mov_b64_e32 v[44:45], v[162:163]
	v_mov_b64_e32 v[46:47], v[164:165]
	v_mov_b64_e32 v[40:41], v[166:167]
	v_mov_b64_e32 v[42:43], v[168:169]
	v_cndmask_b32_e64 v2, v62, v80, s[8:9]
	v_ashrrev_i32_e32 v0, 2, v2
	v_ashrrev_i32_e32 v1, 31, v0
	v_lshlrev_b64 v[0:1], 11, v[0:1]
	v_lshlrev_b32_e32 v2, 9, v2
	v_lshl_add_u64 v[0:1], s[16:17], 0, v[0:1]
	v_and_b32_e32 v2, 0x600, v2
	v_add_u32_e32 v79, s37, v62
	v_lshl_add_u64 v[0:1], v[0:1], 0, v[2:3]
	v_cmp_gt_i32_e64 s[6:7], s81, v79
	v_lshl_add_u64 v[0:1], v[0:1], 0, v[220:221]
	v_mov_b64_e32 v[36:37], v[170:171]
	v_mov_b64_e32 v[38:39], v[172:173]
	v_mov_b64_e32 v[32:33], v[174:175]
	v_mov_b64_e32 v[34:35], v[176:177]
	v_cndmask_b32_e64 v2, v62, v79, s[6:7]
	v_ashrrev_i32_e32 v0, 2, v2
	v_ashrrev_i32_e32 v1, 31, v0
	v_lshlrev_b64 v[0:1], 11, v[0:1]
	v_lshlrev_b32_e32 v2, 9, v2
	s_mul_i32 s2, s60, 0xa0
	v_lshl_add_u64 v[0:1], s[16:17], 0, v[0:1]
	v_and_b32_e32 v2, 0x600, v2
	v_add_u32_e32 v78, s2, v62
	v_lshl_add_u64 v[0:1], v[0:1], 0, v[2:3]
	v_cmp_gt_i32_e64 s[4:5], s81, v78
	v_lshl_add_u64 v[0:1], v[0:1], 0, v[220:221]
	v_mov_b64_e32 v[28:29], v[178:179]
	v_mov_b64_e32 v[30:31], v[180:181]
	v_mov_b64_e32 v[24:25], v[182:183]
	v_mov_b64_e32 v[26:27], v[184:185]
	v_cndmask_b32_e64 v2, v62, v78, s[4:5]
	v_ashrrev_i32_e32 v0, 2, v2
	v_ashrrev_i32_e32 v1, 31, v0
	v_lshlrev_b64 v[0:1], 11, v[0:1]
	v_lshlrev_b32_e32 v2, 9, v2
	s_mul_i32 s2, s60, 0xc0
	v_lshl_add_u64 v[0:1], s[16:17], 0, v[0:1]
	v_and_b32_e32 v2, 0x600, v2
	v_add_u32_e32 v76, s2, v62
	v_lshl_add_u64 v[0:1], v[0:1], 0, v[2:3]
	v_cmp_gt_i32_e64 s[2:3], s81, v76
	v_lshl_add_u64 v[0:1], v[0:1], 0, v[220:221]
	v_mov_b64_e32 v[20:21], v[186:187]
	v_mov_b64_e32 v[22:23], v[188:189]
	v_mov_b64_e32 v[16:17], v[190:191]
	v_mov_b64_e32 v[18:19], v[192:193]
	v_cndmask_b32_e64 v2, v62, v76, s[2:3]
	v_ashrrev_i32_e32 v0, 2, v2
	v_ashrrev_i32_e32 v1, 31, v0
	v_lshlrev_b64 v[0:1], 11, v[0:1]
	v_lshlrev_b32_e32 v2, 9, v2
	s_mul_i32 s12, s60, 0xe0
	v_lshl_add_u64 v[0:1], s[16:17], 0, v[0:1]
	v_and_b32_e32 v2, 0x600, v2
	v_add_u32_e32 v75, s12, v62
	v_lshl_add_u64 v[0:1], v[0:1], 0, v[2:3]
	v_cmp_gt_i32_e32 vcc, s81, v75
	v_lshl_add_u64 v[0:1], v[0:1], 0, v[220:221]
	v_mov_b64_e32 v[12:13], v[194:195]
	v_mov_b64_e32 v[14:15], v[196:197]
	v_mov_b64_e32 v[8:9], v[198:199]
	v_mov_b64_e32 v[10:11], v[200:201]
	v_cndmask_b32_e32 v2, v62, v75, vcc
	v_ashrrev_i32_e32 v0, 2, v2
	v_ashrrev_i32_e32 v1, 31, v0
	v_lshlrev_b64 v[0:1], 11, v[0:1]
	v_lshlrev_b32_e32 v2, 9, v2
	v_lshl_add_u64 v[0:1], s[16:17], 0, v[0:1]
	v_and_b32_e32 v2, 0x600, v2
	v_lshl_add_u64 v[0:1], v[0:1], 0, v[2:3]
	v_lshl_add_u64 v[0:1], v[0:1], 0, v[220:221]
	v_mov_b64_e32 v[4:5], v[202:203]
	v_mov_b64_e32 v[6:7], v[204:205]
	s_nop 0
	v_mov_b64_e32 v[0:1], v[206:207]
	v_mov_b64_e32 v[2:3], v[208:209]
	s_waitcnt vmcnt(15)
	v_lshlrev_b32_e32 v60, 16, v67
	v_and_b32_e32 v61, 0xffff0000, v67
	v_lshlrev_b32_e32 v94, 16, v66
	v_and_b32_e32 v95, 0xffff0000, v66
	s_waitcnt vmcnt(14)
; __device__ __forceinline__ void unpack8(const v4u r, float* x) { x[0] = bflo(r.x); x[1] = bfhi(r.x); x[2] = bflo(r.y); x[3] = bfhi(r.y); x[4] = bflo(r.z); x[5] = bfhi(r.z); x[6] = bflo(r.w); x[7] = bfhi(r.w); }
; __device__ __forceinline__ v4u pack8(const float* x) { v4u o; o.x = pk2(x[0], x[1]); o.y = pk2(x[2], x[3]); o.z = pk2(x[4], x[5]); o.w = pk2(x[6], x[7]); return o; }
; __device__ __forceinline__ float red16(float v) { v = red8(v); v += dpp_<0x140, 0xF>(0.f, v); return v; }
; __device__ __forceinline__ size_t tl(int row, int col, int K) { return (size_t)(row >> 8) * ((size_t)256 * K) + (size_t)(col >> 6) * (256 * 64) + (size_t)((row & 255) * 64 + (col & 63)); }
; __device__ __forceinline__ void attn_post(const u16* O, u16* YC, const float* dlam, const float* dnorm, float lambda_init, int gt, int nthreads, int lane) {
;     ...
;         for (int q = 0; q < 8; ++q) { const int item = item0 + q * stride; const int row = item >> 2, hh = item & 3; float a[8], b[8], d[8]; float ss = 0.f;
;             unpack8(ra[q], a); unpack8(rb[q], b);
; #pragma unroll
;             for (int i = 0; i < 8; ++i) { d[i] = a[i] - lam * b[i]; ss += d[i] * d[i]; }
;             ss = red16(ss);
;             const float r = rsqrtf(ss * (1.0f / 128.0f) + EPS);
; #pragma unroll
;             for (int i = 0; i < 8; ++i) d[i] *= r * gn[i];
;             if (item < MH * 4) *(v4u*)(YC + (size_t)(hh >> 1) * MH * 256 + tl(row, (hh & 1) * 128 + sub * 8, 256)) = pack8(d); }
	v_lshlrev_b32_e32 v66, 16, v84
	v_and_b32_e32 v67, 0xffff0000, v84
	v_pk_fma_f32 v[66:67], v[58:59], v[66:67], v[94:95] neg_lo:[1,0,0] neg_hi:[1,0,0]
	v_lshlrev_b32_e32 v94, 16, v65
	v_and_b32_e32 v95, 0xffff0000, v65
	v_lshlrev_b32_e32 v98, 16, v64
	v_and_b32_e32 v99, 0xffff0000, v64
	v_lshlrev_b32_e32 v64, 16, v82
	v_and_b32_e32 v65, 0xffff0000, v82
	v_lshlrev_b32_e32 v96, 16, v83
	v_and_b32_e32 v97, 0xffff0000, v83
	v_pk_fma_f32 v[64:65], v[58:59], v[64:65], v[98:99] neg_lo:[1,0,0] neg_hi:[1,0,0]
	v_pk_fma_f32 v[94:95], v[58:59], v[96:97], v[94:95] neg_lo:[1,0,0] neg_hi:[1,0,0]
	v_pk_mul_f32 v[82:83], v[64:65], v[64:65]
	v_pk_mul_f32 v[96:97], v[94:95], v[94:95]
	v_add_f32_e32 v63, v82, v83
	v_add_f32_e32 v63, v96, v63
	v_lshlrev_b32_e32 v68, 16, v85
	v_and_b32_e32 v69, 0xffff0000, v85
	v_pk_mul_f32 v[84:85], v[66:67], v[66:67]
	v_add_f32_e32 v63, v97, v63
	v_pk_fma_f32 v[60:61], v[58:59], v[68:69], v[60:61] neg_lo:[1,0,0] neg_hi:[1,0,0]
	v_add_f32_e32 v63, v84, v63
	v_pk_mul_f32 v[68:69], v[60:61], v[60:61]
	v_add_f32_e32 v63, v85, v63
	v_add_f32_e32 v63, v68, v63
	v_add_f32_e32 v63, v69, v63
	v_ashrrev_i32_e32 v62, 10, v62
	s_nop 0
	v_add_f32_dpp v63, v63, v63 quad_perm:[1,0,3,2] row_mask:0xf bank_mask:0xf bound_ctrl:1
	s_nop 1
	v_add_f32_dpp v63, v63, v63 quad_perm:[2,3,0,1] row_mask:0xf bank_mask:0xf bound_ctrl:1
	s_nop 1
	v_add_f32_dpp v63, v63, v63 row_half_mirror row_mask:0xf bank_mask:0xf bound_ctrl:1
	s_nop 1
	v_add_f32_dpp v63, v63, v63 row_mirror row_mask:0xf bank_mask:0xf bound_ctrl:1
	v_fmamk_f32 v63, v63, 0x3c000000, v235
	s_nop 1
	v_rsq_f32_e32 v68, v63
	s_nop 0
	s_nop 0
	v_pk_mul_f32 v[82:83], v[50:51], v[68:69] op_sel_hi:[1,0]
	v_pk_mul_f32 v[84:85], v[54:55], v[68:69] op_sel_hi:[1,0]
	v_pk_mul_f32 v[64:65], v[64:65], v[82:83]
	v_pk_mul_f32 v[82:83], v[52:53], v[68:69] op_sel_hi:[1,0]
	v_pk_mul_f32 v[68:69], v[56:57], v[68:69] op_sel_hi:[1,0]
	v_pk_mul_f32 v[66:67], v[66:67], v[84:85]
	v_pk_mul_f32 v[60:61], v[60:61], v[68:69]
	v_and_or_b32 v68, v71, s90, v48
	v_cvt_pk_bf16_f32 v66, v66, v67
	v_cvt_pk_bf16_f32 v67, v60, v61
	v_and_b32_e32 v60, 0x400000, v72
	v_lshlrev_b32_e32 v68, 8, v68
	v_lshlrev_b32_e32 v220, 1, v60
	v_ashrrev_i32_e32 v63, 31, v62
	v_and_b32_e32 v77, 0xc000, v68
	v_and_b32_e32 v68, 0x3fc0, v70
	v_lshl_add_u64 v[60:61], s[18:19], 0, v[220:221]
	v_or3_b32 v68, v49, v68, v77
	v_lshlrev_b64 v[62:63], 17, v[62:63]
	v_pk_mul_f32 v[82:83], v[94:95], v[82:83]
	v_lshl_add_u64 v[62:63], v[60:61], 0, v[62:63]
	v_lshlrev_b32_e32 v220, 1, v68
	v_cvt_pk_bf16_f32 v64, v64, v65
	v_cvt_pk_bf16_f32 v65, v82, v83
	v_lshl_add_u64 v[62:63], v[62:63], 0, v[220:221]
	global_store_dwordx4 v[62:63], v[64:67], off
	s_waitcnt vmcnt(14)
	v_lshlrev_b32_e32 v62, 16, v86
	v_and_b32_e32 v63, 0xffff0000, v86
	s_waitcnt vmcnt(13)
	v_lshlrev_b32_e32 v64, 16, v90
	v_and_b32_e32 v65, 0xffff0000, v90
	v_pk_fma_f32 v[62:63], v[58:59], v[64:65], v[62:63] neg_lo:[1,0,0] neg_hi:[1,0,0]
	v_lshlrev_b32_e32 v64, 16, v87
	v_and_b32_e32 v65, 0xffff0000, v87
	v_lshlrev_b32_e32 v66, 16, v91
	v_and_b32_e32 v67, 0xffff0000, v91
	v_pk_mul_f32 v[82:83], v[62:63], v[62:63]
	v_pk_fma_f32 v[64:65], v[58:59], v[66:67], v[64:65] neg_lo:[1,0,0] neg_hi:[1,0,0]
	v_lshlrev_b32_e32 v66, 16, v88
	v_pk_mul_f32 v[84:85], v[64:65], v[64:65]
	v_and_b32_e32 v67, 0xffff0000, v88
	v_lshlrev_b32_e32 v68, 16, v92
	v_and_b32_e32 v69, 0xffff0000, v92
	v_add_f32_e32 v82, v82, v83
	v_pk_fma_f32 v[66:67], v[58:59], v[68:69], v[66:67] neg_lo:[1,0,0] neg_hi:[1,0,0]
	v_add_f32_e32 v82, v84, v82
	v_pk_mul_f32 v[86:87], v[66:67], v[66:67]
	v_lshlrev_b32_e32 v68, 16, v89
	v_and_b32_e32 v69, 0xffff0000, v89
	v_lshlrev_b32_e32 v88, 16, v93
	v_and_b32_e32 v89, 0xffff0000, v93
	v_add_f32_e32 v82, v85, v82
	v_pk_fma_f32 v[68:69], v[58:59], v[88:89], v[68:69] neg_lo:[1,0,0] neg_hi:[1,0,0]
	v_add_f32_e32 v82, v86, v82
	v_pk_mul_f32 v[88:89], v[68:69], v[68:69]
	v_add_f32_e32 v82, v87, v82
	v_add_f32_e32 v82, v88, v82
	v_add_f32_e32 v82, v89, v82
	v_mov_b32_e32 v83, v221
	s_nop 0
	v_add_f32_dpp v82, v82, v82 quad_perm:[1,0,3,2] row_mask:0xf bank_mask:0xf bound_ctrl:1
	s_nop 1
	v_add_f32_dpp v82, v82, v82 quad_perm:[2,3,0,1] row_mask:0xf bank_mask:0xf bound_ctrl:1
	s_nop 1
	v_add_f32_dpp v82, v82, v82 row_half_mirror row_mask:0xf bank_mask:0xf bound_ctrl:1
	s_nop 1
	v_mov_b32_dpp v83, v82 row_mirror row_mask:0xf bank_mask:0xf
	s_and_saveexec_b64 s[12:13], s[0:1]
	s_cbranch_execz .LBB0_984
	v_add_f32_e32 v82, v82, v83
	v_fmamk_f32 v82, v82, 0x3c000000, v235
	s_nop 0
	v_rsq_f32_e32 v82, v82
	s_nop 0
	s_nop 0
	v_pk_mul_f32 v[84:85], v[50:51], v[82:83] op_sel_hi:[1,0]
	s_nop 0
	v_pk_mul_f32 v[62:63], v[62:63], v[84:85]
	v_pk_mul_f32 v[84:85], v[52:53], v[82:83] op_sel_hi:[1,0]
	v_cvt_pk_bf16_f32 v62, v62, v63
	v_pk_mul_f32 v[64:65], v[64:65], v[84:85]
	v_pk_mul_f32 v[84:85], v[54:55], v[82:83] op_sel_hi:[1,0]
	v_pk_mul_f32 v[82:83], v[56:57], v[82:83] op_sel_hi:[1,0]
	v_pk_mul_f32 v[66:67], v[66:67], v[84:85]
	v_pk_mul_f32 v[68:69], v[68:69], v[82:83]
	v_cvt_pk_bf16_f32 v63, v64, v65
	v_cvt_pk_bf16_f32 v64, v66, v67
	v_cvt_pk_bf16_f32 v65, v68, v69
	v_ashrrev_i32_e32 v66, 10, v74
	v_add_u32_e32 v68, s40, v70
	v_ashrrev_i32_e32 v67, 31, v66
	v_and_b32_e32 v68, 0x3fc0, v68
	v_or3_b32 v68, v68, v77, v49
	v_lshlrev_b64 v[66:67], 17, v[66:67]
	v_lshl_add_u64 v[66:67], v[60:61], 0, v[66:67]
	v_lshlrev_b32_e32 v220, 1, v68
	v_lshl_add_u64 v[66:67], v[66:67], 0, v[220:221]
	global_store_dwordx4 v[66:67], v[62:65], off
; __device__ __forceinline__ void unpack8(const v4u r, float* x) { x[0] = bflo(r.x); x[1] = bfhi(r.x); x[2] = bflo(r.y); x[3] = bfhi(r.y); x[4] = bflo(r.z); x[5] = bfhi(r.z); x[6] = bflo(r.w); x[7] = bfhi(r.w); }
; __device__ __forceinline__ v4u pack8(const float* x) { v4u o; o.x = pk2(x[0], x[1]); o.y = pk2(x[2], x[3]); o.z = pk2(x[4], x[5]); o.w = pk2(x[6], x[7]); return o; }
; __device__ __forceinline__ float red16(float v) { v = red8(v); v += dpp_<0x140, 0xF>(0.f, v); return v; }
; __device__ __forceinline__ size_t tl(int row, int col, int K) { return (size_t)(row >> 8) * ((size_t)256 * K) + (size_t)(col >> 6) * (256 * 64) + (size_t)((row & 255) * 64 + (col & 63)); }
; __device__ __forceinline__ void attn_post(const u16* O, u16* YC, const float* dlam, const float* dnorm, float lambda_init, int gt, int nthreads, int lane) {
;     ...
;         for (int q = 0; q < 8; ++q) { const int item = item0 + q * stride; const int row = item >> 2, hh = item & 3; float a[8], b[8], d[8]; float ss = 0.f;
;             unpack8(ra[q], a); unpack8(rb[q], b);
; #pragma unroll
;             for (int i = 0; i < 8; ++i) { d[i] = a[i] - lam * b[i]; ss += d[i] * d[i]; }
;             ss = red16(ss);
;             const float r = rsqrtf(ss * (1.0f / 128.0f) + EPS);
; #pragma unroll
;             for (int i = 0; i < 8; ++i) d[i] *= r * gn[i];
;             if (item < MH * 4) *(v4u*)(YC + (size_t)(hh >> 1) * MH * 256 + tl(row, (hh & 1) * 128 + sub * 8, 256)) = pack8(d); }
.LBB0_984:
	s_or_b64 exec, exec, s[12:13]
	s_waitcnt vmcnt(12)
	v_lshlrev_b32_e32 v62, 16, v44
	v_and_b32_e32 v63, 0xffff0000, v44
	s_waitcnt vmcnt(11)
	v_lshlrev_b32_e32 v64, 16, v40
	v_and_b32_e32 v65, 0xffff0000, v40
	v_pk_fma_f32 v[62:63], v[58:59], v[64:65], v[62:63] neg_lo:[1,0,0] neg_hi:[1,0,0]
	v_lshlrev_b32_e32 v44, 16, v45
	v_and_b32_e32 v45, 0xffff0000, v45
	v_lshlrev_b32_e32 v40, 16, v41
	v_and_b32_e32 v41, 0xffff0000, v41
	v_pk_mul_f32 v[64:65], v[62:63], v[62:63]
	v_pk_fma_f32 v[40:41], v[58:59], v[40:41], v[44:45] neg_lo:[1,0,0] neg_hi:[1,0,0]
	v_lshlrev_b32_e32 v44, 16, v46
	v_pk_mul_f32 v[66:67], v[40:41], v[40:41]
	v_and_b32_e32 v45, 0xffff0000, v46
	v_lshlrev_b32_e32 v68, 16, v42
	v_and_b32_e32 v69, 0xffff0000, v42
	v_add_f32_e32 v64, v64, v65
	v_pk_fma_f32 v[44:45], v[58:59], v[68:69], v[44:45] neg_lo:[1,0,0] neg_hi:[1,0,0]
	v_add_f32_e32 v64, v66, v64
	v_pk_mul_f32 v[68:69], v[44:45], v[44:45]
	v_lshlrev_b32_e32 v46, 16, v47
	v_and_b32_e32 v47, 0xffff0000, v47
	v_lshlrev_b32_e32 v42, 16, v43
	v_and_b32_e32 v43, 0xffff0000, v43
	v_add_f32_e32 v64, v67, v64
	v_pk_fma_f32 v[42:43], v[58:59], v[42:43], v[46:47] neg_lo:[1,0,0] neg_hi:[1,0,0]
	v_add_f32_e32 v64, v68, v64
	v_pk_mul_f32 v[46:47], v[42:43], v[42:43]
	v_add_f32_e32 v64, v69, v64
	v_add_f32_e32 v46, v46, v64
	v_add_f32_e32 v46, v47, v46
	v_mov_b32_e32 v47, v221
	s_nop 0
	v_add_f32_dpp v46, v46, v46 quad_perm:[1,0,3,2] row_mask:0xf bank_mask:0xf bound_ctrl:1
	s_nop 1
	v_add_f32_dpp v46, v46, v46 quad_perm:[2,3,0,1] row_mask:0xf bank_mask:0xf bound_ctrl:1
	s_nop 1
	v_add_f32_dpp v46, v46, v46 row_half_mirror row_mask:0xf bank_mask:0xf bound_ctrl:1
	s_nop 1
	v_mov_b32_dpp v47, v46 row_mirror row_mask:0xf bank_mask:0xf
	s_and_saveexec_b64 s[12:13], s[10:11]
	s_cbranch_execz .LBB0_986
	v_add_f32_e32 v46, v46, v47
	v_fmamk_f32 v46, v46, 0x3c000000, v235
	s_nop 0
	v_rsq_f32_e32 v46, v46
	s_nop 0
	s_nop 0
	v_pk_mul_f32 v[64:65], v[50:51], v[46:47] op_sel_hi:[1,0]
	s_nop 0
	v_pk_mul_f32 v[62:63], v[62:63], v[64:65]
	v_pk_mul_f32 v[64:65], v[52:53], v[46:47] op_sel_hi:[1,0]
	s_nop 0
	v_pk_mul_f32 v[64:65], v[40:41], v[64:65]
	v_pk_mul_f32 v[40:41], v[54:55], v[46:47] op_sel_hi:[1,0]
	s_nop 0
	v_pk_mul_f32 v[44:45], v[44:45], v[40:41]
	v_pk_mul_f32 v[40:41], v[56:57], v[46:47] op_sel_hi:[1,0]
	s_nop 0
	v_pk_mul_f32 v[46:47], v[42:43], v[40:41]
	v_cvt_pk_bf16_f32 v42, v44, v45
	v_cvt_pk_bf16_f32 v43, v46, v47
	v_ashrrev_i32_e32 v44, 10, v81
	v_add_u32_e32 v46, s33, v70
	v_ashrrev_i32_e32 v45, 31, v44
	v_and_b32_e32 v46, 0x3fc0, v46
	v_or3_b32 v46, v46, v49, v77
	v_lshlrev_b64 v[44:45], 17, v[44:45]
	v_lshl_add_u64 v[44:45], v[60:61], 0, v[44:45]
	v_lshlrev_b32_e32 v220, 1, v46
	v_cvt_pk_bf16_f32 v40, v62, v63
	v_cvt_pk_bf16_f32 v41, v64, v65
	v_lshl_add_u64 v[44:45], v[44:45], 0, v[220:221]
	global_store_dwordx4 v[44:45], v[40:43], off
.LBB0_986:
	s_or_b64 exec, exec, s[12:13]
	s_waitcnt vmcnt(10)
	v_lshlrev_b32_e32 v40, 16, v36
	v_and_b32_e32 v41, 0xffff0000, v36
	s_waitcnt vmcnt(9)
	v_lshlrev_b32_e32 v42, 16, v32
	v_and_b32_e32 v43, 0xffff0000, v32
	v_pk_fma_f32 v[40:41], v[58:59], v[42:43], v[40:41] neg_lo:[1,0,0] neg_hi:[1,0,0]
	v_lshlrev_b32_e32 v36, 16, v37
	v_and_b32_e32 v37, 0xffff0000, v37
	v_lshlrev_b32_e32 v32, 16, v33
	v_and_b32_e32 v33, 0xffff0000, v33
	v_pk_mul_f32 v[42:43], v[40:41], v[40:41]
	v_pk_fma_f32 v[32:33], v[58:59], v[32:33], v[36:37] neg_lo:[1,0,0] neg_hi:[1,0,0]
	v_lshlrev_b32_e32 v36, 16, v38
	v_pk_mul_f32 v[44:45], v[32:33], v[32:33]
	v_and_b32_e32 v37, 0xffff0000, v38
	v_lshlrev_b32_e32 v46, 16, v34
	v_and_b32_e32 v47, 0xffff0000, v34
	v_add_f32_e32 v42, v42, v43
	v_pk_fma_f32 v[36:37], v[58:59], v[46:47], v[36:37] neg_lo:[1,0,0] neg_hi:[1,0,0]
	v_add_f32_e32 v42, v44, v42
	v_pk_mul_f32 v[46:47], v[36:37], v[36:37]
	v_lshlrev_b32_e32 v38, 16, v39
	v_and_b32_e32 v39, 0xffff0000, v39
	v_lshlrev_b32_e32 v34, 16, v35
	v_and_b32_e32 v35, 0xffff0000, v35
	v_add_f32_e32 v42, v45, v42
	v_pk_fma_f32 v[34:35], v[58:59], v[34:35], v[38:39] neg_lo:[1,0,0] neg_hi:[1,0,0]
	v_add_f32_e32 v42, v46, v42
	v_pk_mul_f32 v[38:39], v[34:35], v[34:35]
	v_add_f32_e32 v42, v47, v42
	v_add_f32_e32 v38, v38, v42
	v_add_f32_e32 v38, v39, v38
	v_mov_b32_e32 v39, v221
	s_nop 0
	v_add_f32_dpp v38, v38, v38 quad_perm:[1,0,3,2] row_mask:0xf bank_mask:0xf bound_ctrl:1
	s_nop 1
	v_add_f32_dpp v38, v38, v38 quad_perm:[2,3,0,1] row_mask:0xf bank_mask:0xf bound_ctrl:1
	s_nop 1
	v_add_f32_dpp v38, v38, v38 row_half_mirror row_mask:0xf bank_mask:0xf bound_ctrl:1
	s_nop 1
	v_mov_b32_dpp v39, v38 row_mirror row_mask:0xf bank_mask:0xf
	s_and_saveexec_b64 s[10:11], s[8:9]
	s_cbranch_execz .LBB0_988
	v_add_f32_e32 v38, v38, v39
	v_fmamk_f32 v38, v38, 0x3c000000, v235
	s_nop 0
	v_rsq_f32_e32 v38, v38
	s_nop 0
	s_nop 0
	v_pk_mul_f32 v[42:43], v[50:51], v[38:39] op_sel_hi:[1,0]
	s_mul_i32 s0, s60, 0x600
	v_pk_mul_f32 v[40:41], v[40:41], v[42:43]
	v_pk_mul_f32 v[42:43], v[52:53], v[38:39] op_sel_hi:[1,0]
	s_nop 0
	v_pk_mul_f32 v[42:43], v[32:33], v[42:43]
	v_pk_mul_f32 v[32:33], v[54:55], v[38:39] op_sel_hi:[1,0]
	s_nop 0
	v_pk_mul_f32 v[36:37], v[36:37], v[32:33]
	v_pk_mul_f32 v[32:33], v[56:57], v[38:39] op_sel_hi:[1,0]
	s_nop 0
	v_pk_mul_f32 v[38:39], v[34:35], v[32:33]
	v_cvt_pk_bf16_f32 v34, v36, v37
	v_cvt_pk_bf16_f32 v35, v38, v39
	v_ashrrev_i32_e32 v36, 10, v80
	v_add_u32_e32 v38, s0, v70
	v_ashrrev_i32_e32 v37, 31, v36
	v_and_b32_e32 v38, 0x3fc0, v38
	v_or3_b32 v38, v38, v77, v49
	v_lshlrev_b64 v[36:37], 17, v[36:37]
	v_lshl_add_u64 v[36:37], v[60:61], 0, v[36:37]
	v_lshlrev_b32_e32 v220, 1, v38
	v_cvt_pk_bf16_f32 v32, v40, v41
	v_cvt_pk_bf16_f32 v33, v42, v43
	v_lshl_add_u64 v[36:37], v[36:37], 0, v[220:221]
	global_store_dwordx4 v[36:37], v[32:35], off
; __device__ __forceinline__ void unpack8(const v4u r, float* x) { x[0] = bflo(r.x); x[1] = bfhi(r.x); x[2] = bflo(r.y); x[3] = bfhi(r.y); x[4] = bflo(r.z); x[5] = bfhi(r.z); x[6] = bflo(r.w); x[7] = bfhi(r.w); }
; __device__ __forceinline__ v4u pack8(const float* x) { v4u o; o.x = pk2(x[0], x[1]); o.y = pk2(x[2], x[3]); o.z = pk2(x[4], x[5]); o.w = pk2(x[6], x[7]); return o; }
; __device__ __forceinline__ float red16(float v) { v = red8(v); v += dpp_<0x140, 0xF>(0.f, v); return v; }
; __device__ __forceinline__ size_t tl(int row, int col, int K) { return (size_t)(row >> 8) * ((size_t)256 * K) + (size_t)(col >> 6) * (256 * 64) + (size_t)((row & 255) * 64 + (col & 63)); }
; __device__ __forceinline__ void attn_post(const u16* O, u16* YC, const float* dlam, const float* dnorm, float lambda_init, int gt, int nthreads, int lane) {
;     ...
;         for (int q = 0; q < 8; ++q) { const int item = item0 + q * stride; const int row = item >> 2, hh = item & 3; float a[8], b[8], d[8]; float ss = 0.f;
;             unpack8(ra[q], a); unpack8(rb[q], b);
; #pragma unroll
;             for (int i = 0; i < 8; ++i) { d[i] = a[i] - lam * b[i]; ss += d[i] * d[i]; }
;             ss = red16(ss);
;             const float r = rsqrtf(ss * (1.0f / 128.0f) + EPS);
; #pragma unroll
;             for (int i = 0; i < 8; ++i) d[i] *= r * gn[i];
;             if (item < MH * 4) *(v4u*)(YC + (size_t)(hh >> 1) * MH * 256 + tl(row, (hh & 1) * 128 + sub * 8, 256)) = pack8(d); }
.LBB0_988:
	s_or_b64 exec, exec, s[10:11]
	s_waitcnt vmcnt(8)
	v_lshlrev_b32_e32 v32, 16, v28
	v_and_b32_e32 v33, 0xffff0000, v28
	s_waitcnt vmcnt(7)
	v_lshlrev_b32_e32 v34, 16, v24
	v_and_b32_e32 v35, 0xffff0000, v24
	v_pk_fma_f32 v[32:33], v[58:59], v[34:35], v[32:33] neg_lo:[1,0,0] neg_hi:[1,0,0]
	v_lshlrev_b32_e32 v28, 16, v29
	v_and_b32_e32 v29, 0xffff0000, v29
	v_lshlrev_b32_e32 v24, 16, v25
	v_and_b32_e32 v25, 0xffff0000, v25
	v_pk_mul_f32 v[34:35], v[32:33], v[32:33]
	v_pk_fma_f32 v[24:25], v[58:59], v[24:25], v[28:29] neg_lo:[1,0,0] neg_hi:[1,0,0]
	v_lshlrev_b32_e32 v28, 16, v30
	v_pk_mul_f32 v[36:37], v[24:25], v[24:25]
	v_and_b32_e32 v29, 0xffff0000, v30
	v_lshlrev_b32_e32 v38, 16, v26
	v_and_b32_e32 v39, 0xffff0000, v26
	v_add_f32_e32 v34, v34, v35
	v_pk_fma_f32 v[28:29], v[58:59], v[38:39], v[28:29] neg_lo:[1,0,0] neg_hi:[1,0,0]
	v_add_f32_e32 v34, v36, v34
	v_pk_mul_f32 v[38:39], v[28:29], v[28:29]
	v_lshlrev_b32_e32 v30, 16, v31
	v_and_b32_e32 v31, 0xffff0000, v31
	v_lshlrev_b32_e32 v26, 16, v27
	v_and_b32_e32 v27, 0xffff0000, v27
	v_add_f32_e32 v34, v37, v34
	v_pk_fma_f32 v[26:27], v[58:59], v[26:27], v[30:31] neg_lo:[1,0,0] neg_hi:[1,0,0]
	v_add_f32_e32 v34, v38, v34
	v_pk_mul_f32 v[30:31], v[26:27], v[26:27]
	v_add_f32_e32 v34, v39, v34
	v_add_f32_e32 v30, v30, v34
	v_add_f32_e32 v30, v31, v30
	v_mov_b32_e32 v31, v221
	s_nop 0
	v_add_f32_dpp v30, v30, v30 quad_perm:[1,0,3,2] row_mask:0xf bank_mask:0xf bound_ctrl:1
	s_nop 1
	v_add_f32_dpp v30, v30, v30 quad_perm:[2,3,0,1] row_mask:0xf bank_mask:0xf bound_ctrl:1
	s_nop 1
	v_add_f32_dpp v30, v30, v30 row_half_mirror row_mask:0xf bank_mask:0xf bound_ctrl:1
	s_nop 1
	v_mov_b32_dpp v31, v30 row_mirror row_mask:0xf bank_mask:0xf
	s_and_saveexec_b64 s[8:9], s[6:7]
	s_cbranch_execz .LBB0_990
	v_add_f32_e32 v30, v30, v31
	v_fmamk_f32 v30, v30, 0x3c000000, v235
	s_nop 0
	v_rsq_f32_e32 v30, v30
	s_nop 0
	s_nop 0
	v_pk_mul_f32 v[34:35], v[50:51], v[30:31] op_sel_hi:[1,0]
	s_nop 0
	v_pk_mul_f32 v[32:33], v[32:33], v[34:35]
	v_pk_mul_f32 v[34:35], v[52:53], v[30:31] op_sel_hi:[1,0]
	s_nop 0
	v_pk_mul_f32 v[34:35], v[24:25], v[34:35]
	v_pk_mul_f32 v[24:25], v[54:55], v[30:31] op_sel_hi:[1,0]
	s_nop 0
	v_pk_mul_f32 v[28:29], v[28:29], v[24:25]
	v_pk_mul_f32 v[24:25], v[56:57], v[30:31] op_sel_hi:[1,0]
	s_nop 0
	v_pk_mul_f32 v[30:31], v[26:27], v[24:25]
	v_cvt_pk_bf16_f32 v26, v28, v29
	v_cvt_pk_bf16_f32 v27, v30, v31
	v_ashrrev_i32_e32 v28, 10, v79
	v_add_u32_e32 v30, s39, v70
	v_ashrrev_i32_e32 v29, 31, v28
	v_and_b32_e32 v30, 0x3fc0, v30
	v_or3_b32 v30, v30, v49, v77
	v_lshlrev_b64 v[28:29], 17, v[28:29]
	v_lshl_add_u64 v[28:29], v[60:61], 0, v[28:29]
	v_lshlrev_b32_e32 v220, 1, v30
	v_cvt_pk_bf16_f32 v24, v32, v33
	v_cvt_pk_bf16_f32 v25, v34, v35
	v_lshl_add_u64 v[28:29], v[28:29], 0, v[220:221]
	global_store_dwordx4 v[28:29], v[24:27], off
.LBB0_990:
	s_or_b64 exec, exec, s[8:9]
	s_waitcnt vmcnt(6)
	v_lshlrev_b32_e32 v24, 16, v20
	v_and_b32_e32 v25, 0xffff0000, v20
	s_waitcnt vmcnt(5)
	v_lshlrev_b32_e32 v26, 16, v16
	v_and_b32_e32 v27, 0xffff0000, v16
	v_pk_fma_f32 v[24:25], v[58:59], v[26:27], v[24:25] neg_lo:[1,0,0] neg_hi:[1,0,0]
	v_lshlrev_b32_e32 v20, 16, v21
	v_and_b32_e32 v21, 0xffff0000, v21
	v_lshlrev_b32_e32 v16, 16, v17
	v_and_b32_e32 v17, 0xffff0000, v17
	v_pk_mul_f32 v[26:27], v[24:25], v[24:25]
	v_pk_fma_f32 v[16:17], v[58:59], v[16:17], v[20:21] neg_lo:[1,0,0] neg_hi:[1,0,0]
	v_lshlrev_b32_e32 v20, 16, v22
	v_pk_mul_f32 v[28:29], v[16:17], v[16:17]
	v_and_b32_e32 v21, 0xffff0000, v22
	v_lshlrev_b32_e32 v30, 16, v18
	v_and_b32_e32 v31, 0xffff0000, v18
	v_add_f32_e32 v26, v26, v27
	v_pk_fma_f32 v[20:21], v[58:59], v[30:31], v[20:21] neg_lo:[1,0,0] neg_hi:[1,0,0]
	v_add_f32_e32 v26, v28, v26
	v_pk_mul_f32 v[30:31], v[20:21], v[20:21]
	v_lshlrev_b32_e32 v22, 16, v23
	v_and_b32_e32 v23, 0xffff0000, v23
	v_lshlrev_b32_e32 v18, 16, v19
	v_and_b32_e32 v19, 0xffff0000, v19
	v_add_f32_e32 v26, v29, v26
	v_pk_fma_f32 v[18:19], v[58:59], v[18:19], v[22:23] neg_lo:[1,0,0] neg_hi:[1,0,0]
	v_add_f32_e32 v26, v30, v26
	v_pk_mul_f32 v[22:23], v[18:19], v[18:19]
	v_add_f32_e32 v26, v31, v26
	v_add_f32_e32 v22, v22, v26
	v_add_f32_e32 v22, v23, v22
	v_mov_b32_e32 v23, v221
	s_nop 0
	v_add_f32_dpp v22, v22, v22 quad_perm:[1,0,3,2] row_mask:0xf bank_mask:0xf bound_ctrl:1
	s_nop 1
	v_add_f32_dpp v22, v22, v22 quad_perm:[2,3,0,1] row_mask:0xf bank_mask:0xf bound_ctrl:1
	s_nop 1
	v_add_f32_dpp v22, v22, v22 row_half_mirror row_mask:0xf bank_mask:0xf bound_ctrl:1
	s_nop 1
	v_mov_b32_dpp v23, v22 row_mirror row_mask:0xf bank_mask:0xf
	s_and_saveexec_b64 s[6:7], s[4:5]
	s_cbranch_execz .LBB0_992
	v_add_f32_e32 v22, v22, v23
	v_fmamk_f32 v22, v22, 0x3c000000, v235
	s_nop 0
	v_rsq_f32_e32 v22, v22
	s_nop 0
	s_nop 0
	v_pk_mul_f32 v[26:27], v[50:51], v[22:23] op_sel_hi:[1,0]
	s_mul_i32 s0, s60, 0xa00
	v_pk_mul_f32 v[24:25], v[24:25], v[26:27]
	v_pk_mul_f32 v[26:27], v[52:53], v[22:23] op_sel_hi:[1,0]
	s_nop 0
	v_pk_mul_f32 v[26:27], v[16:17], v[26:27]
	v_pk_mul_f32 v[16:17], v[54:55], v[22:23] op_sel_hi:[1,0]
	s_nop 0
	v_pk_mul_f32 v[20:21], v[20:21], v[16:17]
	v_pk_mul_f32 v[16:17], v[56:57], v[22:23] op_sel_hi:[1,0]
	s_nop 0
	v_pk_mul_f32 v[22:23], v[18:19], v[16:17]
	v_cvt_pk_bf16_f32 v18, v20, v21
	v_cvt_pk_bf16_f32 v19, v22, v23
	v_ashrrev_i32_e32 v20, 10, v78
	v_add_u32_e32 v22, s0, v70
	v_ashrrev_i32_e32 v21, 31, v20
	v_and_b32_e32 v22, 0x3fc0, v22
	v_or3_b32 v22, v22, v77, v49
	v_lshlrev_b64 v[20:21], 17, v[20:21]
	v_lshl_add_u64 v[20:21], v[60:61], 0, v[20:21]
	v_lshlrev_b32_e32 v220, 1, v22
	v_cvt_pk_bf16_f32 v16, v24, v25
	v_cvt_pk_bf16_f32 v17, v26, v27
	v_lshl_add_u64 v[20:21], v[20:21], 0, v[220:221]
	global_store_dwordx4 v[20:21], v[16:19], off
; __device__ __forceinline__ void unpack8(const v4u r, float* x) { x[0] = bflo(r.x); x[1] = bfhi(r.x); x[2] = bflo(r.y); x[3] = bfhi(r.y); x[4] = bflo(r.z); x[5] = bfhi(r.z); x[6] = bflo(r.w); x[7] = bfhi(r.w); }
; __device__ __forceinline__ v4u pack8(const float* x) { v4u o; o.x = pk2(x[0], x[1]); o.y = pk2(x[2], x[3]); o.z = pk2(x[4], x[5]); o.w = pk2(x[6], x[7]); return o; }
; __device__ __forceinline__ float red16(float v) { v = red8(v); v += dpp_<0x140, 0xF>(0.f, v); return v; }
; __device__ __forceinline__ size_t tl(int row, int col, int K) { return (size_t)(row >> 8) * ((size_t)256 * K) + (size_t)(col >> 6) * (256 * 64) + (size_t)((row & 255) * 64 + (col & 63)); }
; __device__ __forceinline__ void attn_post(const u16* O, u16* YC, const float* dlam, const float* dnorm, float lambda_init, int gt, int nthreads, int lane) {
;     ...
;         for (int q = 0; q < 8; ++q) { const int item = item0 + q * stride; const int row = item >> 2, hh = item & 3; float a[8], b[8], d[8]; float ss = 0.f;
;             unpack8(ra[q], a); unpack8(rb[q], b);
; #pragma unroll
;             for (int i = 0; i < 8; ++i) { d[i] = a[i] - lam * b[i]; ss += d[i] * d[i]; }
;             ss = red16(ss);
;             const float r = rsqrtf(ss * (1.0f / 128.0f) + EPS);
; #pragma unroll
;             for (int i = 0; i < 8; ++i) d[i] *= r * gn[i];
;             if (item < MH * 4) *(v4u*)(YC + (size_t)(hh >> 1) * MH * 256 + tl(row, (hh & 1) * 128 + sub * 8, 256)) = pack8(d); }
.LBB0_992:
	s_or_b64 exec, exec, s[6:7]
	s_waitcnt vmcnt(4)
	v_lshlrev_b32_e32 v16, 16, v12
	v_and_b32_e32 v17, 0xffff0000, v12
	s_waitcnt vmcnt(3)
	v_lshlrev_b32_e32 v18, 16, v8
	v_and_b32_e32 v19, 0xffff0000, v8
	v_pk_fma_f32 v[16:17], v[58:59], v[18:19], v[16:17] neg_lo:[1,0,0] neg_hi:[1,0,0]
	v_lshlrev_b32_e32 v12, 16, v13
	v_and_b32_e32 v13, 0xffff0000, v13
	v_lshlrev_b32_e32 v8, 16, v9
	v_and_b32_e32 v9, 0xffff0000, v9
	v_pk_mul_f32 v[18:19], v[16:17], v[16:17]
	v_pk_fma_f32 v[8:9], v[58:59], v[8:9], v[12:13] neg_lo:[1,0,0] neg_hi:[1,0,0]
	v_lshlrev_b32_e32 v12, 16, v14
	v_pk_mul_f32 v[20:21], v[8:9], v[8:9]
	v_and_b32_e32 v13, 0xffff0000, v14
	v_lshlrev_b32_e32 v22, 16, v10
	v_and_b32_e32 v23, 0xffff0000, v10
	v_add_f32_e32 v18, v18, v19
	v_pk_fma_f32 v[12:13], v[58:59], v[22:23], v[12:13] neg_lo:[1,0,0] neg_hi:[1,0,0]
	v_add_f32_e32 v18, v20, v18
	v_pk_mul_f32 v[22:23], v[12:13], v[12:13]
	v_lshlrev_b32_e32 v14, 16, v15
	v_and_b32_e32 v15, 0xffff0000, v15
	v_lshlrev_b32_e32 v10, 16, v11
	v_and_b32_e32 v11, 0xffff0000, v11
	v_add_f32_e32 v18, v21, v18
	v_pk_fma_f32 v[10:11], v[58:59], v[10:11], v[14:15] neg_lo:[1,0,0] neg_hi:[1,0,0]
	v_add_f32_e32 v18, v22, v18
	v_pk_mul_f32 v[14:15], v[10:11], v[10:11]
	v_add_f32_e32 v18, v23, v18
	v_add_f32_e32 v14, v14, v18
	v_add_f32_e32 v14, v15, v14
	v_mov_b32_e32 v15, v221
	s_nop 0
	v_add_f32_dpp v14, v14, v14 quad_perm:[1,0,3,2] row_mask:0xf bank_mask:0xf bound_ctrl:1
	s_nop 1
	v_add_f32_dpp v14, v14, v14 quad_perm:[2,3,0,1] row_mask:0xf bank_mask:0xf bound_ctrl:1
	s_nop 1
	v_add_f32_dpp v14, v14, v14 row_half_mirror row_mask:0xf bank_mask:0xf bound_ctrl:1
	s_nop 1
	v_mov_b32_dpp v15, v14 row_mirror row_mask:0xf bank_mask:0xf
	s_and_saveexec_b64 s[4:5], s[2:3]
	s_cbranch_execz .LBB0_994
	v_add_f32_e32 v14, v14, v15
	v_fmamk_f32 v14, v14, 0x3c000000, v235
	s_nop 0
	v_rsq_f32_e32 v14, v14
	s_nop 0
	s_nop 0
	v_pk_mul_f32 v[18:19], v[50:51], v[14:15] op_sel_hi:[1,0]
	s_mul_i32 s0, s60, 0xc00
	v_pk_mul_f32 v[16:17], v[16:17], v[18:19]
	v_pk_mul_f32 v[18:19], v[52:53], v[14:15] op_sel_hi:[1,0]
	s_nop 0
	v_pk_mul_f32 v[18:19], v[8:9], v[18:19]
	v_pk_mul_f32 v[8:9], v[54:55], v[14:15] op_sel_hi:[1,0]
	s_nop 0
	v_pk_mul_f32 v[12:13], v[12:13], v[8:9]
	v_pk_mul_f32 v[8:9], v[56:57], v[14:15] op_sel_hi:[1,0]
	s_nop 0
	v_pk_mul_f32 v[14:15], v[10:11], v[8:9]
	v_cvt_pk_bf16_f32 v10, v12, v13
	v_cvt_pk_bf16_f32 v11, v14, v15
	v_ashrrev_i32_e32 v12, 10, v76
	v_add_u32_e32 v14, s0, v70
	v_ashrrev_i32_e32 v13, 31, v12
	v_and_b32_e32 v14, 0x3fc0, v14
	v_or3_b32 v14, v14, v49, v77
	v_lshlrev_b64 v[12:13], 17, v[12:13]
	v_lshl_add_u64 v[12:13], v[60:61], 0, v[12:13]
	v_lshlrev_b32_e32 v220, 1, v14
	v_cvt_pk_bf16_f32 v8, v16, v17
	v_cvt_pk_bf16_f32 v9, v18, v19
	v_lshl_add_u64 v[12:13], v[12:13], 0, v[220:221]
	global_store_dwordx4 v[12:13], v[8:11], off
.LBB0_994:
	s_or_b64 exec, exec, s[4:5]
	s_waitcnt vmcnt(2)
	v_lshlrev_b32_e32 v8, 16, v4
	v_and_b32_e32 v9, 0xffff0000, v4
	s_waitcnt vmcnt(1)
	v_lshlrev_b32_e32 v10, 16, v0
	v_and_b32_e32 v11, 0xffff0000, v0
	v_pk_fma_f32 v[8:9], v[58:59], v[10:11], v[8:9] neg_lo:[1,0,0] neg_hi:[1,0,0]
	v_lshlrev_b32_e32 v4, 16, v5
	v_and_b32_e32 v5, 0xffff0000, v5
	v_lshlrev_b32_e32 v0, 16, v1
	v_and_b32_e32 v1, 0xffff0000, v1
	v_pk_mul_f32 v[10:11], v[8:9], v[8:9]
	v_pk_fma_f32 v[0:1], v[58:59], v[0:1], v[4:5] neg_lo:[1,0,0] neg_hi:[1,0,0]
	v_lshlrev_b32_e32 v4, 16, v6
	v_pk_mul_f32 v[12:13], v[0:1], v[0:1]
	v_and_b32_e32 v5, 0xffff0000, v6
	v_lshlrev_b32_e32 v14, 16, v2
	v_and_b32_e32 v15, 0xffff0000, v2
	v_add_f32_e32 v10, v10, v11
	v_pk_fma_f32 v[4:5], v[58:59], v[14:15], v[4:5] neg_lo:[1,0,0] neg_hi:[1,0,0]
	v_add_f32_e32 v10, v12, v10
	v_pk_mul_f32 v[14:15], v[4:5], v[4:5]
	v_lshlrev_b32_e32 v6, 16, v7
	v_and_b32_e32 v7, 0xffff0000, v7
	v_lshlrev_b32_e32 v2, 16, v3
	v_and_b32_e32 v3, 0xffff0000, v3
	v_add_f32_e32 v10, v13, v10
	v_pk_fma_f32 v[2:3], v[58:59], v[2:3], v[6:7] neg_lo:[1,0,0] neg_hi:[1,0,0]
	v_add_f32_e32 v10, v14, v10
	v_pk_mul_f32 v[6:7], v[2:3], v[2:3]
	v_add_f32_e32 v10, v15, v10
	v_add_f32_e32 v6, v6, v10
	v_add_f32_e32 v6, v7, v6
	v_mov_b32_e32 v7, v221
	s_nop 0
	v_add_f32_dpp v6, v6, v6 quad_perm:[1,0,3,2] row_mask:0xf bank_mask:0xf bound_ctrl:1
	s_nop 1
	v_add_f32_dpp v6, v6, v6 quad_perm:[2,3,0,1] row_mask:0xf bank_mask:0xf bound_ctrl:1
	s_nop 1
	v_add_f32_dpp v6, v6, v6 row_half_mirror row_mask:0xf bank_mask:0xf bound_ctrl:1
	s_nop 1
	v_mov_b32_dpp v7, v6 row_mirror row_mask:0xf bank_mask:0xf
	s_and_saveexec_b64 s[0:1], vcc
	s_cbranch_execz .LBB0_981
	v_add_f32_e32 v6, v6, v7
	v_fmamk_f32 v6, v6, 0x3c000000, v235
	s_mul_i32 s2, s60, 0xe00
	v_rsq_f32_e32 v6, v6
	s_nop 0
	s_nop 0
	v_pk_mul_f32 v[10:11], v[50:51], v[6:7] op_sel_hi:[1,0]
	s_nop 0
	v_pk_mul_f32 v[8:9], v[8:9], v[10:11]
	v_pk_mul_f32 v[10:11], v[52:53], v[6:7] op_sel_hi:[1,0]
	s_nop 0
	v_pk_mul_f32 v[10:11], v[0:1], v[10:11]
	v_pk_mul_f32 v[0:1], v[54:55], v[6:7] op_sel_hi:[1,0]
	s_nop 0
	v_pk_mul_f32 v[4:5], v[4:5], v[0:1]
	v_pk_mul_f32 v[0:1], v[56:57], v[6:7] op_sel_hi:[1,0]
	s_nop 0
	v_pk_mul_f32 v[6:7], v[2:3], v[0:1]
	v_cvt_pk_bf16_f32 v2, v4, v5
	v_cvt_pk_bf16_f32 v3, v6, v7
	v_ashrrev_i32_e32 v4, 10, v75
	v_add_u32_e32 v6, s2, v70
	v_ashrrev_i32_e32 v5, 31, v4
	v_and_b32_e32 v6, 0x3fc0, v6
	v_or3_b32 v6, v6, v77, v49
	v_lshlrev_b64 v[4:5], 17, v[4:5]
	v_lshl_add_u64 v[4:5], v[60:61], 0, v[4:5]
	v_lshlrev_b32_e32 v220, 1, v6
	v_cvt_pk_bf16_f32 v0, v8, v9
	v_cvt_pk_bf16_f32 v1, v10, v11
	v_lshl_add_u64 v[4:5], v[4:5], 0, v[220:221]
	global_store_dwordx4 v[4:5], v[0:3], off
	s_branch .LBB0_981

; __device__ __forceinline__ float rstd_from_quarter(const v4f a, int ln) {
;     float s = (a.x + a.y) + (a.z + a.w);
;     s += __int_as_float(__builtin_amdgcn_ds_bpermute((ln ^ 16) << 2, __float_as_int(s))); s += __int_as_float(__builtin_amdgcn_ds_bpermute((ln ^ 32) << 2, __float_as_int(s)));
;     return rsqrtf(s * (1.0f / DM) + EPS);
; }
;     __device__ __forceinline__ void operator()(const f32x4 (&acc)[2][2][4][2], const Unit& u, int wr, int wc, int, int) const {
;     ...
;                 const int row = row0 + ai * HALF + m * 16; const float rs = rstd_from_quarter(pq[mm], fq * 16 + fr);
;                 float v0[8], v1[8];
; #pragma unroll
;                 for (int n = 0; n < 2; ++n)
; #pragma unroll
;                     for (int i = 0; i < 4; ++i) { v0[n * 4 + i] = acc[ai][0][m][n][i] * rs; v1[n * 4 + i] = acc[ai][1][m][n][i] * rs; }
;                 bf16_t* zr = Z + (size_t)row * ZP + (tile < 5 ? tile : 0) * 256;
;                 const int bl_ = row >> 12, sq_ = row & (SEQ - 1);
;                 if (tile >= 5 && tile <= 8) {
;                     const v4f c0 = cs[mm][0], c1 = cs[mm][1], s0 = cs[mm][2], s1 = cs[mm][3];
;                     const float cc[8] = {c0.x, c0.y, c0.z, c0.w, c1.x, c1.y, c1.z, c1.w}, sn[8] = {s0.x, s0.y, s0.z, s0.w, s1.x, s1.y, s1.z, s1.w};
;                     const float qs = tile < 7 ? QC2 : 1.0f;
;                     float o0[8], o1[8];
; #pragma unroll
;                     for (int i = 0; i < 8; ++i) { o0[i] = (v0[i] * cc[i] - v1[i] * sn[i]) * qs; o1[i] = (v1[i] * cc[i] + v0[i] * sn[i]) * qs; }
;                     bf16_t* dst = (tile < 7 ? QC : KC) + ((size_t)((bl_ * 8 + ((tile - 5) & 1) * 4 + wc) * SEQ + sq_)) * 64 + 8 * fq;
;                     *(u32x4*)(dst) = pack8(o0);
;                     *(u32x4*)(dst + 32) = pack8(o1);
;                 } else if (tile == 23) {
;                     if (wc == 0 && fq == 0) {
;                         float* mo = mif + (size_t)row * 8;
;                         *(v4f*)(mo) = (v4f){v0[0] + gate_b[0], v0[1] + gate_b[1], v0[2] + gate_b[2], v0[3] + gate_b[3]};
;                         *(v4f*)(mo + 4) = (v4f){v0[4] + gate_b[4], v0[5] + gate_b[5], v0[6] + gate_b[6], v0[7] + gate_b[7]};
;                     }
;                 } else if (tile == 9 || tile == 10) {
.LBB0_1137:
	v_lshlrev_b64 v[218:219], 6, v[180:181]
	v_lshl_add_u64 v[218:219], v[182:183], 0, v[218:219]
	global_load_dwordx4 v[206:209], v[218:219], off offset:2048
	global_load_dwordx4 v[210:213], v[218:219], off offset:3072
	v_add_co_u32_e32 v218, vcc, 0x2000, v218
	s_nop 1
	v_addc_co_u32_e32 v219, vcc, 0, v219, vcc
	global_load_dwordx4 v[214:217], v[218:219], off
	global_load_dwordx4 v[222:225], v[218:219], off offset:1024
	global_load_dwordx4 v[226:229], v[218:219], off offset:2048
	global_load_dwordx4 v[240:243], v[218:219], off offset:3072
	v_lshlrev_b32_e32 v191, 2, v191
	v_lshlrev_b32_e32 v220, 3, v190
	v_bitop3_b32 v194, v191, 64, v244 bitop3:0x6c
	v_bitop3_b32 v195, v191, s90, v244 bitop3:0x6c
	v_cmp_eq_u32_e32 vcc, 0, v190
	s_waitcnt vmcnt(0)
	v_mov_b32_e32 v190, v165
	v_mov_b32_e32 v191, v166
	v_mov_b32_e32 v165, v167
	v_pk_add_f32 v[164:165], v[190:191], v[164:165]
	s_lshl_b32 s4, s8, 8
	v_add_f32_e32 v164, v164, v165
	ds_bpermute_b32 v165, v194, v164
	s_cmp_lt_i32 s8, 5
	s_cselect_b32 s88, s4, 0
	s_ashr_i32 s89, s88, 31
	s_cmp_lg_u32 s8, 23
	s_waitcnt lgkmcnt(0)
	v_add_f32_e32 v164, v164, v165
	ds_bpermute_b32 v165, v195, v164
	s_cselect_b64 s[96:97], -1, 0
	s_add_i32 s5, s8, -9
	s_cmp_gt_u32 s5, 1
	s_cselect_b64 s[92:93], -1, 0
	s_waitcnt lgkmcnt(0)
	v_add_f32_e32 v164, v164, v165
	s_cmp_lt_i32 s8, 11
	v_fmamk_f32 v164, v164, 0x3a800000, v235
	s_cselect_b64 s[90:91], -1, 0
	s_and_b64 s[84:85], s[72:73], vcc
	s_add_i32 s86, s4, 0xfffff500
	v_rsq_f32_e32 v196, v164
	s_lshl_b32 s77, s8, 14
	s_ashr_i32 s87, s86, 31
	s_add_i32 s77, s77, s0
	s_cmp_lt_u32 s8, 7
	s_cselect_b64 s[4:5], -1, 0
	s_ashr_i32 s9, s9, 12
	s_nop 0
	s_lshl_b32 s40, s9, 15
	s_add_i32 s40, s40, s77
	v_pk_mul_f32 v[166:167], v[156:157], v[196:197] op_sel_hi:[1,0]
	v_pk_mul_f32 v[190:191], v[148:149], v[196:197] op_sel_hi:[1,0]
	v_pk_mul_f32 v[158:159], v[158:159], v[196:197] op_sel_hi:[1,0]
	v_pk_mul_f32 v[164:165], v[150:151], v[196:197] op_sel_hi:[1,0]
	v_pk_mul_f32 v[152:153], v[152:153], v[196:197] op_sel_hi:[1,0]
	v_pk_mul_f32 v[156:157], v[144:145], v[196:197] op_sel_hi:[1,0]
	v_pk_mul_f32 v[148:149], v[154:155], v[196:197] op_sel_hi:[1,0]
	v_pk_mul_f32 v[150:151], v[146:147], v[196:197] op_sel_hi:[1,0]
	v_and_b32_e32 v147, 0xfcf, v180
	s_mov_b64 s[10:11], -1
	s_and_b64 vcc, exec, s[94:95]
	s_cbranch_vccz .LBB0_1153
	s_and_b64 vcc, exec, s[96:97]
	s_cbranch_vccz .LBB0_1148
	s_and_b64 vcc, exec, s[92:93]
	s_cbranch_vccz .LBB0_1145
	v_mov_b64_e32 v[144:145], s[12:13]
	v_mad_i64_i32 v[144:145], s[10:11], v180, s29, v[144:145]
	s_mov_b64 s[10:11], -1
	s_and_b64 vcc, exec, s[90:91]
	s_cbranch_vccz .LBB0_1142
	v_lshl_add_u64 v[154:155], s[88:89], 1, v[144:145]
	s_lshl_b32 s30, s68, 1
	v_lshl_add_u64 v[154:155], v[154:155], 0, s[30:31]
	v_lshlrev_b32_e32 v200, 1, v220
	v_mov_b32_e32 v201, v221
	v_cvt_pk_bf16_f32 v196, v166, v167
	v_cvt_pk_bf16_f32 v197, v158, v159
	v_cvt_pk_bf16_f32 v198, v152, v153
	v_cvt_pk_bf16_f32 v199, v148, v149
	v_lshl_add_u64 v[154:155], v[154:155], 0, v[200:201]
	global_store_dwordx4 v[154:155], v[196:199], off
	s_mov_b64 s[10:11], 0
	s_nop 0
	v_cvt_pk_bf16_f32 v196, v190, v191
	v_cvt_pk_bf16_f32 v197, v164, v165
	v_cvt_pk_bf16_f32 v198, v156, v157
	v_cvt_pk_bf16_f32 v199, v150, v151
	global_store_dwordx4 v[154:155], v[196:199], off offset:256

; __device__ __forceinline__ float rstd_from_quarter(const v4f a, int ln) {
;     float s = (a.x + a.y) + (a.z + a.w);
;     s += __int_as_float(__builtin_amdgcn_ds_bpermute((ln ^ 16) << 2, __float_as_int(s))); s += __int_as_float(__builtin_amdgcn_ds_bpermute((ln ^ 32) << 2, __float_as_int(s)));
;     return rsqrtf(s * (1.0f / DM) + EPS);
; }
;     __device__ __forceinline__ void operator()(const f32x4 (&acc)[2][2][4][2], const Unit& u, int wr, int wc, int, int) const {
;     ...
;                 const int row = row0 + ai * HALF + m * 16; const float rs = rstd_from_quarter(pq[mm], fq * 16 + fr);
;                 float v0[8], v1[8];
; #pragma unroll
;                 for (int n = 0; n < 2; ++n)
; #pragma unroll
;                     for (int i = 0; i < 4; ++i) { v0[n * 4 + i] = acc[ai][0][m][n][i] * rs; v1[n * 4 + i] = acc[ai][1][m][n][i] * rs; }
;                 bf16_t* zr = Z + (size_t)row * ZP + (tile < 5 ? tile : 0) * 256;
;                 const int bl_ = row >> 12, sq_ = row & (SEQ - 1);
;                 if (tile >= 5 && tile <= 8) {
;                     const v4f c0 = cs[mm][0], c1 = cs[mm][1], s0 = cs[mm][2], s1 = cs[mm][3];
;                     const float cc[8] = {c0.x, c0.y, c0.z, c0.w, c1.x, c1.y, c1.z, c1.w}, sn[8] = {s0.x, s0.y, s0.z, s0.w, s1.x, s1.y, s1.z, s1.w};
;                     const float qs = tile < 7 ? QC2 : 1.0f;
;                     float o0[8], o1[8];
; #pragma unroll
;                     for (int i = 0; i < 8; ++i) { o0[i] = (v0[i] * cc[i] - v1[i] * sn[i]) * qs; o1[i] = (v1[i] * cc[i] + v0[i] * sn[i]) * qs; }
;                     bf16_t* dst = (tile < 7 ? QC : KC) + ((size_t)((bl_ * 8 + ((tile - 5) & 1) * 4 + wc) * SEQ + sq_)) * 64 + 8 * fq;
;                     *(u32x4*)(dst) = pack8(o0);
;                     *(u32x4*)(dst + 32) = pack8(o1);
;                 } else if (tile == 23) {
;                     if (wc == 0 && fq == 0) {
;                         float* mo = mif + (size_t)row * 8;
;                         *(v4f*)(mo) = (v4f){v0[0] + gate_b[0], v0[1] + gate_b[1], v0[2] + gate_b[2], v0[3] + gate_b[3]};
;                         *(v4f*)(mo + 4) = (v4f){v0[4] + gate_b[4], v0[5] + gate_b[5], v0[6] + gate_b[6], v0[7] + gate_b[7]};
;                     }
;                 } else if (tile == 9 || tile == 10) {
.LBB0_1177:
	v_mov_b32_e32 v132, v206
	v_mov_b32_e32 v133, v207
	v_mov_b32_e32 v134, v208
	v_mov_b32_e32 v135, v209
	v_mov_b32_e32 v140, v133
	v_mov_b32_e32 v141, v134
	v_mov_b32_e32 v133, v135
	v_pk_add_f32 v[132:133], v[140:141], v[132:133]
	s_mov_b64 s[22:23], -1
	v_add_f32_e32 v132, v132, v133
	ds_bpermute_b32 v133, v194, v132
	s_waitcnt lgkmcnt(0)
	v_add_f32_e32 v132, v132, v133
	ds_bpermute_b32 v133, v195, v132
	s_waitcnt lgkmcnt(0)
	v_add_f32_e32 v132, v132, v133
	v_fmamk_f32 v132, v132, 0x3a800000, v235
	s_nop 1
	v_rsq_f32_e32 v140, v132
	s_nop 0
	s_nop 0
	v_pk_mul_f32 v[132:133], v[124:125], v[140:141] op_sel_hi:[1,0]
	v_pk_mul_f32 v[134:135], v[116:117], v[140:141] op_sel_hi:[1,0]
	v_pk_mul_f32 v[124:125], v[126:127], v[140:141] op_sel_hi:[1,0]
	v_pk_mul_f32 v[126:127], v[118:119], v[140:141] op_sel_hi:[1,0]
	v_pk_mul_f32 v[116:117], v[120:121], v[140:141] op_sel_hi:[1,0]
	v_pk_mul_f32 v[118:119], v[112:113], v[140:141] op_sel_hi:[1,0]
	v_pk_mul_f32 v[112:113], v[122:123], v[140:141] op_sel_hi:[1,0]
	v_pk_mul_f32 v[114:115], v[114:115], v[140:141] op_sel_hi:[1,0]
	v_and_b32_e32 v122, 0xfef, v138
	s_and_b64 vcc, exec, s[10:11]
	s_cbranch_vccnz .LBB0_1193
	s_and_b64 vcc, exec, s[8:9]
	s_cbranch_vccnz .LBB0_1188
	s_andn2_b64 vcc, exec, s[92:93]
	s_cbranch_vccnz .LBB0_1185
	v_mov_b64_e32 v[120:121], s[12:13]
	v_mad_i64_i32 v[120:121], s[22:23], v138, s29, v[120:121]
	s_andn2_b64 vcc, exec, s[90:91]
	s_mov_b64 s[22:23], -1
	s_cbranch_vccnz .LBB0_1182
	v_lshl_add_u64 v[148:149], s[88:89], 1, v[120:121]
	s_lshl_b32 s30, s68, 1
	v_lshl_add_u64 v[148:149], v[148:149], 0, s[30:31]
	v_mov_b32_e32 v145, v221
	v_cvt_pk_bf16_f32 v140, v132, v133
	v_cvt_pk_bf16_f32 v141, v124, v125
	v_cvt_pk_bf16_f32 v142, v116, v117
	v_cvt_pk_bf16_f32 v143, v112, v113
	v_lshl_add_u64 v[148:149], v[148:149], 0, v[144:145]
	global_store_dwordx4 v[148:149], v[140:143], off
	s_mov_b64 s[22:23], 0
	s_nop 0
	v_cvt_pk_bf16_f32 v140, v134, v135
	v_cvt_pk_bf16_f32 v141, v126, v127
	v_cvt_pk_bf16_f32 v142, v118, v119
	v_cvt_pk_bf16_f32 v143, v114, v115
	global_store_dwordx4 v[148:149], v[140:143], off offset:256

; __device__ __forceinline__ float rstd_from_quarter(const v4f a, int ln) {
;     float s = (a.x + a.y) + (a.z + a.w);
;     s += __int_as_float(__builtin_amdgcn_ds_bpermute((ln ^ 16) << 2, __float_as_int(s))); s += __int_as_float(__builtin_amdgcn_ds_bpermute((ln ^ 32) << 2, __float_as_int(s)));
;     return rsqrtf(s * (1.0f / DM) + EPS);
; }
;     __device__ __forceinline__ void operator()(const f32x4 (&acc)[2][2][4][2], const Unit& u, int wr, int wc, int, int) const {
;     ...
;                 const int row = row0 + ai * HALF + m * 16; const float rs = rstd_from_quarter(pq[mm], fq * 16 + fr);
;                 float v0[8], v1[8];
; #pragma unroll
;                 for (int n = 0; n < 2; ++n)
; #pragma unroll
;                     for (int i = 0; i < 4; ++i) { v0[n * 4 + i] = acc[ai][0][m][n][i] * rs; v1[n * 4 + i] = acc[ai][1][m][n][i] * rs; }
;                 bf16_t* zr = Z + (size_t)row * ZP + (tile < 5 ? tile : 0) * 256;
;                 const int bl_ = row >> 12, sq_ = row & (SEQ - 1);
;                 if (tile >= 5 && tile <= 8) {
;                     const v4f c0 = cs[mm][0], c1 = cs[mm][1], s0 = cs[mm][2], s1 = cs[mm][3];
;                     const float cc[8] = {c0.x, c0.y, c0.z, c0.w, c1.x, c1.y, c1.z, c1.w}, sn[8] = {s0.x, s0.y, s0.z, s0.w, s1.x, s1.y, s1.z, s1.w};
;                     const float qs = tile < 7 ? QC2 : 1.0f;
;                     float o0[8], o1[8];
; #pragma unroll
;                     for (int i = 0; i < 8; ++i) { o0[i] = (v0[i] * cc[i] - v1[i] * sn[i]) * qs; o1[i] = (v1[i] * cc[i] + v0[i] * sn[i]) * qs; }
;                     bf16_t* dst = (tile < 7 ? QC : KC) + ((size_t)((bl_ * 8 + ((tile - 5) & 1) * 4 + wc) * SEQ + sq_)) * 64 + 8 * fq;
;                     *(u32x4*)(dst) = pack8(o0);
;                     *(u32x4*)(dst + 32) = pack8(o1);
;                 } else if (tile == 23) {
;                     if (wc == 0 && fq == 0) {
;                         float* mo = mif + (size_t)row * 8;
;                         *(v4f*)(mo) = (v4f){v0[0] + gate_b[0], v0[1] + gate_b[1], v0[2] + gate_b[2], v0[3] + gate_b[3]};
;                         *(v4f*)(mo + 4) = (v4f){v0[4] + gate_b[4], v0[5] + gate_b[5], v0[6] + gate_b[6], v0[7] + gate_b[7]};
;                     }
;                 } else if (tile == 9 || tile == 10) {
.LBB0_1195:
	v_mov_b32_e32 v128, v210
	v_mov_b32_e32 v129, v211
	v_mov_b32_e32 v130, v212
	v_mov_b32_e32 v131, v213
	s_nop 0
	v_mov_b32_e32 v112, v129
	v_mov_b32_e32 v113, v130
	v_mov_b32_e32 v129, v131
	v_pk_add_f32 v[112:113], v[112:113], v[128:129]
	v_and_b32_e32 v116, 0xfff, v136
	v_add_f32_e32 v112, v112, v113
	ds_bpermute_b32 v113, v194, v112
	s_mov_b64 s[22:23], -1
	s_waitcnt lgkmcnt(0)
	v_add_f32_e32 v112, v112, v113
	ds_bpermute_b32 v113, v195, v112
	s_waitcnt lgkmcnt(0)
	v_add_f32_e32 v112, v112, v113
	v_fmamk_f32 v112, v112, 0x3a800000, v235
	s_nop 1
	v_rsq_f32_e32 v118, v112
	s_nop 0
	s_nop 0
	v_pk_mul_f32 v[112:113], v[108:109], v[118:119] op_sel_hi:[1,0]
	v_pk_mul_f32 v[114:115], v[100:101], v[118:119] op_sel_hi:[1,0]
	v_pk_mul_f32 v[108:109], v[110:111], v[118:119] op_sel_hi:[1,0]
	v_pk_mul_f32 v[110:111], v[102:103], v[118:119] op_sel_hi:[1,0]
	v_pk_mul_f32 v[100:101], v[104:105], v[118:119] op_sel_hi:[1,0]
	v_pk_mul_f32 v[102:103], v[96:97], v[118:119] op_sel_hi:[1,0]
	v_pk_mul_f32 v[96:97], v[106:107], v[118:119] op_sel_hi:[1,0]
	v_pk_mul_f32 v[98:99], v[98:99], v[118:119] op_sel_hi:[1,0]
	s_and_b64 vcc, exec, s[10:11]
	s_cbranch_vccnz .LBB0_1211
	s_and_b64 vcc, exec, s[8:9]
	s_cbranch_vccnz .LBB0_1206
	s_andn2_b64 vcc, exec, s[92:93]
	s_cbranch_vccnz .LBB0_1203
	v_mov_b64_e32 v[104:105], s[12:13]
	v_mad_i64_i32 v[104:105], s[22:23], v136, s29, v[104:105]
	s_andn2_b64 vcc, exec, s[90:91]
	s_mov_b64 s[22:23], -1
	s_cbranch_vccnz .LBB0_1200
	v_lshl_add_u64 v[106:107], s[88:89], 1, v[104:105]
	s_lshl_b32 s30, s68, 1
	v_lshl_add_u64 v[106:107], v[106:107], 0, s[30:31]
	v_mov_b32_e32 v145, v221
	v_cvt_pk_bf16_f32 v118, v112, v113
	v_cvt_pk_bf16_f32 v119, v108, v109
	v_cvt_pk_bf16_f32 v120, v100, v101
	v_cvt_pk_bf16_f32 v121, v96, v97
	v_lshl_add_u64 v[106:107], v[106:107], 0, v[144:145]
	global_store_dwordx4 v[106:107], v[118:121], off
	s_mov_b64 s[22:23], 0
	s_nop 0
	v_cvt_pk_bf16_f32 v118, v114, v115
	v_cvt_pk_bf16_f32 v119, v110, v111
	v_cvt_pk_bf16_f32 v120, v102, v103
	v_cvt_pk_bf16_f32 v121, v98, v99
	global_store_dwordx4 v[106:107], v[118:121], off offset:256

; __device__ __forceinline__ float rstd_from_quarter(const v4f a, int ln) {
;     float s = (a.x + a.y) + (a.z + a.w);
;     s += __int_as_float(__builtin_amdgcn_ds_bpermute((ln ^ 16) << 2, __float_as_int(s))); s += __int_as_float(__builtin_amdgcn_ds_bpermute((ln ^ 32) << 2, __float_as_int(s)));
;     return rsqrtf(s * (1.0f / DM) + EPS);
; }
;     __device__ __forceinline__ void operator()(const f32x4 (&acc)[2][2][4][2], const Unit& u, int wr, int wc, int, int) const {
;     ...
;                 const int row = row0 + ai * HALF + m * 16; const float rs = rstd_from_quarter(pq[mm], fq * 16 + fr);
;                 float v0[8], v1[8];
; #pragma unroll
;                 for (int n = 0; n < 2; ++n)
; #pragma unroll
;                     for (int i = 0; i < 4; ++i) { v0[n * 4 + i] = acc[ai][0][m][n][i] * rs; v1[n * 4 + i] = acc[ai][1][m][n][i] * rs; }
;                 bf16_t* zr = Z + (size_t)row * ZP + (tile < 5 ? tile : 0) * 256;
;                 const int bl_ = row >> 12, sq_ = row & (SEQ - 1);
;                 if (tile >= 5 && tile <= 8) {
;                     const v4f c0 = cs[mm][0], c1 = cs[mm][1], s0 = cs[mm][2], s1 = cs[mm][3];
;                     const float cc[8] = {c0.x, c0.y, c0.z, c0.w, c1.x, c1.y, c1.z, c1.w}, sn[8] = {s0.x, s0.y, s0.z, s0.w, s1.x, s1.y, s1.z, s1.w};
;                     const float qs = tile < 7 ? QC2 : 1.0f;
;                     float o0[8], o1[8];
; #pragma unroll
;                     for (int i = 0; i < 8; ++i) { o0[i] = (v0[i] * cc[i] - v1[i] * sn[i]) * qs; o1[i] = (v1[i] * cc[i] + v0[i] * sn[i]) * qs; }
;                     bf16_t* dst = (tile < 7 ? QC : KC) + ((size_t)((bl_ * 8 + ((tile - 5) & 1) * 4 + wc) * SEQ + sq_)) * 64 + 8 * fq;
;                     *(u32x4*)(dst) = pack8(o0);
;                     *(u32x4*)(dst + 32) = pack8(o1);
;                 } else if (tile == 23) {
;                     if (wc == 0 && fq == 0) {
;                         float* mo = mif + (size_t)row * 8;
;                         *(v4f*)(mo) = (v4f){v0[0] + gate_b[0], v0[1] + gate_b[1], v0[2] + gate_b[2], v0[3] + gate_b[3]};
;                         *(v4f*)(mo + 4) = (v4f){v0[4] + gate_b[4], v0[5] + gate_b[5], v0[6] + gate_b[6], v0[7] + gate_b[7]};
;                     }
;                 } else if (tile == 9 || tile == 10) {
.LBB0_1217:
	v_mov_b32_e32 v100, v214
	v_mov_b32_e32 v101, v215
	v_mov_b32_e32 v102, v216
	v_mov_b32_e32 v103, v217
	v_mov_b32_e32 v110, v101
	v_mov_b32_e32 v111, v102
	v_mov_b32_e32 v101, v103
	v_pk_add_f32 v[100:101], v[110:111], v[100:101]
	v_ashrrev_i32_e32 v109, 12, v106
	v_add_f32_e32 v100, v100, v101
	ds_bpermute_b32 v101, v194, v100
	v_lshl_add_u32 v108, v109, 15, s77
	s_mov_b64 s[94:95], -1
	s_waitcnt lgkmcnt(0)
	v_add_f32_e32 v100, v100, v101
	ds_bpermute_b32 v101, v195, v100
	s_waitcnt lgkmcnt(0)
	v_add_f32_e32 v100, v100, v101
	v_fmamk_f32 v100, v100, 0x3a800000, v235
	s_nop 0
	v_rsq_f32_e32 v110, v100
	s_nop 0
	s_nop 0
	v_pk_mul_f32 v[100:101], v[92:93], v[110:111] op_sel_hi:[1,0]
	v_pk_mul_f32 v[102:103], v[84:85], v[110:111] op_sel_hi:[1,0]
	v_pk_mul_f32 v[92:93], v[94:95], v[110:111] op_sel_hi:[1,0]
	v_pk_mul_f32 v[94:95], v[86:87], v[110:111] op_sel_hi:[1,0]
	v_pk_mul_f32 v[84:85], v[88:89], v[110:111] op_sel_hi:[1,0]
	v_pk_mul_f32 v[86:87], v[80:81], v[110:111] op_sel_hi:[1,0]
	v_pk_mul_f32 v[80:81], v[90:91], v[110:111] op_sel_hi:[1,0]
	v_pk_mul_f32 v[82:83], v[82:83], v[110:111] op_sel_hi:[1,0]
	v_and_b32_e32 v90, 0xfcf, v106
	s_and_b64 vcc, exec, s[10:11]
	s_cbranch_vccnz .LBB0_1233
	s_and_b64 vcc, exec, s[8:9]
	s_mov_b64 s[22:23], -1
	s_cbranch_vccnz .LBB0_1228
	s_andn2_b64 vcc, exec, s[92:93]
	s_cbranch_vccnz .LBB0_1225
	v_mov_b64_e32 v[88:89], s[12:13]
	v_mad_i64_i32 v[88:89], s[22:23], v106, s29, v[88:89]
	s_andn2_b64 vcc, exec, s[90:91]
	s_mov_b64 s[22:23], -1
	s_cbranch_vccnz .LBB0_1222
	v_lshl_add_u64 v[114:115], s[88:89], 1, v[88:89]
	s_lshl_b32 s30, s68, 1
	v_lshl_add_u64 v[114:115], v[114:115], 0, s[30:31]
	v_mov_b32_e32 v145, v221
	v_cvt_pk_bf16_f32 v110, v100, v101
	v_cvt_pk_bf16_f32 v111, v92, v93
	v_cvt_pk_bf16_f32 v112, v84, v85
	v_cvt_pk_bf16_f32 v113, v80, v81
	v_lshl_add_u64 v[114:115], v[114:115], 0, v[144:145]
	global_store_dwordx4 v[114:115], v[110:113], off
	s_mov_b64 s[22:23], 0
	s_nop 0
	v_cvt_pk_bf16_f32 v110, v102, v103
	v_cvt_pk_bf16_f32 v111, v94, v95
	v_cvt_pk_bf16_f32 v112, v86, v87
	v_cvt_pk_bf16_f32 v113, v82, v83
	global_store_dwordx4 v[114:115], v[110:113], off offset:256

; __device__ __forceinline__ float rstd_from_quarter(const v4f a, int ln) {
;     float s = (a.x + a.y) + (a.z + a.w);
;     s += __int_as_float(__builtin_amdgcn_ds_bpermute((ln ^ 16) << 2, __float_as_int(s))); s += __int_as_float(__builtin_amdgcn_ds_bpermute((ln ^ 32) << 2, __float_as_int(s)));
;     return rsqrtf(s * (1.0f / DM) + EPS);
; }
;     __device__ __forceinline__ void operator()(const f32x4 (&acc)[2][2][4][2], const Unit& u, int wr, int wc, int, int) const {
;     ...
;                 const int row = row0 + ai * HALF + m * 16; const float rs = rstd_from_quarter(pq[mm], fq * 16 + fr);
;                 float v0[8], v1[8];
; #pragma unroll
;                 for (int n = 0; n < 2; ++n)
; #pragma unroll
;                     for (int i = 0; i < 4; ++i) { v0[n * 4 + i] = acc[ai][0][m][n][i] * rs; v1[n * 4 + i] = acc[ai][1][m][n][i] * rs; }
;                 bf16_t* zr = Z + (size_t)row * ZP + (tile < 5 ? tile : 0) * 256;
;                 const int bl_ = row >> 12, sq_ = row & (SEQ - 1);
;                 if (tile >= 5 && tile <= 8) {
;                     const v4f c0 = cs[mm][0], c1 = cs[mm][1], s0 = cs[mm][2], s1 = cs[mm][3];
;                     const float cc[8] = {c0.x, c0.y, c0.z, c0.w, c1.x, c1.y, c1.z, c1.w}, sn[8] = {s0.x, s0.y, s0.z, s0.w, s1.x, s1.y, s1.z, s1.w};
;                     const float qs = tile < 7 ? QC2 : 1.0f;
;                     float o0[8], o1[8];
; #pragma unroll
;                     for (int i = 0; i < 8; ++i) { o0[i] = (v0[i] * cc[i] - v1[i] * sn[i]) * qs; o1[i] = (v1[i] * cc[i] + v0[i] * sn[i]) * qs; }
;                     bf16_t* dst = (tile < 7 ? QC : KC) + ((size_t)((bl_ * 8 + ((tile - 5) & 1) * 4 + wc) * SEQ + sq_)) * 64 + 8 * fq;
;                     *(u32x4*)(dst) = pack8(o0);
;                     *(u32x4*)(dst + 32) = pack8(o1);
;                 } else if (tile == 23) {
;                     if (wc == 0 && fq == 0) {
;                         float* mo = mif + (size_t)row * 8;
;                         *(v4f*)(mo) = (v4f){v0[0] + gate_b[0], v0[1] + gate_b[1], v0[2] + gate_b[2], v0[3] + gate_b[3]};
;                         *(v4f*)(mo + 4) = (v4f){v0[4] + gate_b[4], v0[5] + gate_b[5], v0[6] + gate_b[6], v0[7] + gate_b[7]};
;                     }
;                 } else if (tile == 9 || tile == 10) {
.LBB0_1235:
	v_mov_b32_e32 v96, v222
	v_mov_b32_e32 v97, v223
	v_mov_b32_e32 v98, v224
	v_mov_b32_e32 v99, v225
	s_nop 0
	v_mov_b32_e32 v80, v97
	v_mov_b32_e32 v81, v98
	v_mov_b32_e32 v97, v99
	v_pk_add_f32 v[80:81], v[80:81], v[96:97]
	v_and_b32_e32 v84, 0xfdf, v104
	v_add_f32_e32 v80, v80, v81
	ds_bpermute_b32 v81, v194, v80
	s_mov_b64 s[22:23], -1
	s_waitcnt lgkmcnt(0)
	v_add_f32_e32 v80, v80, v81
	ds_bpermute_b32 v81, v195, v80
	s_waitcnt lgkmcnt(0)
	v_add_f32_e32 v80, v80, v81
	v_fmamk_f32 v80, v80, 0x3a800000, v235
	s_nop 1
	v_rsq_f32_e32 v86, v80
	s_nop 0
	s_nop 0
	v_pk_mul_f32 v[80:81], v[76:77], v[86:87] op_sel_hi:[1,0]
	v_pk_mul_f32 v[82:83], v[68:69], v[86:87] op_sel_hi:[1,0]
	v_pk_mul_f32 v[76:77], v[78:79], v[86:87] op_sel_hi:[1,0]
	v_pk_mul_f32 v[78:79], v[70:71], v[86:87] op_sel_hi:[1,0]
	v_pk_mul_f32 v[68:69], v[72:73], v[86:87] op_sel_hi:[1,0]
	v_pk_mul_f32 v[70:71], v[64:65], v[86:87] op_sel_hi:[1,0]
	v_pk_mul_f32 v[64:65], v[74:75], v[86:87] op_sel_hi:[1,0]
	v_pk_mul_f32 v[66:67], v[66:67], v[86:87] op_sel_hi:[1,0]
	s_and_b64 vcc, exec, s[10:11]
	s_cbranch_vccnz .LBB0_1251
	s_and_b64 vcc, exec, s[8:9]
	s_cbranch_vccnz .LBB0_1246
	s_andn2_b64 vcc, exec, s[92:93]
	s_cbranch_vccnz .LBB0_1243
	v_mov_b64_e32 v[72:73], s[12:13]
	v_mad_i64_i32 v[72:73], s[22:23], v104, s29, v[72:73]
	s_andn2_b64 vcc, exec, s[90:91]
	s_mov_b64 s[22:23], -1
	s_cbranch_vccnz .LBB0_1240
	v_lshl_add_u64 v[74:75], s[88:89], 1, v[72:73]
	s_lshl_b32 s30, s68, 1
	v_lshl_add_u64 v[74:75], v[74:75], 0, s[30:31]
	v_mov_b32_e32 v145, v221
	v_cvt_pk_bf16_f32 v90, v80, v81
	v_cvt_pk_bf16_f32 v91, v76, v77
	v_cvt_pk_bf16_f32 v92, v68, v69
	v_cvt_pk_bf16_f32 v93, v64, v65
	v_lshl_add_u64 v[74:75], v[74:75], 0, v[144:145]
	global_store_dwordx4 v[74:75], v[90:93], off
	s_mov_b64 s[22:23], 0
	s_nop 0
	v_cvt_pk_bf16_f32 v90, v82, v83
	v_cvt_pk_bf16_f32 v91, v78, v79
	v_cvt_pk_bf16_f32 v92, v70, v71
	v_cvt_pk_bf16_f32 v93, v66, v67
	global_store_dwordx4 v[74:75], v[90:93], off offset:256

;     __device__ __forceinline__ void operator()(const f32x4 (&acc)[2][2][4][2], const Unit& u, int wr, int wc, int, int) const {
;     ...
;             for (int mm = 0; mm < 2; ++mm) { const int m = (ab & 1) * 2 + mm;
;                 const int row = row0 + ai * HALF + m * 16; const float rs = rstd_from_quarter(pq[mm], fq * 16 + fr);
;                 float v0[8], v1[8];
; #pragma unroll
;                 for (int n = 0; n < 2; ++n)
; #pragma unroll
;                     for (int i = 0; i < 4; ++i) { v0[n * 4 + i] = acc[ai][0][m][n][i] * rs; v1[n * 4 + i] = acc[ai][1][m][n][i] * rs; }
;                 bf16_t* zr = Z + (size_t)row * ZP + (tile < 5 ? tile : 0) * 256;
;                 const int bl_ = row >> 12, sq_ = row & (SEQ - 1);
;                 if (tile >= 5 && tile <= 8) {
;                     const v4f c0 = cs[mm][0], c1 = cs[mm][1], s0 = cs[mm][2], s1 = cs[mm][3];
;                     const float cc[8] = {c0.x, c0.y, c0.z, c0.w, c1.x, c1.y, c1.z, c1.w}, sn[8] = {s0.x, s0.y, s0.z, s0.w, s1.x, s1.y, s1.z, s1.w};
;                     const float qs = tile < 7 ? QC2 : 1.0f;
;                     float o0[8], o1[8];
; #pragma unroll
;                     for (int i = 0; i < 8; ++i) { o0[i] = (v0[i] * cc[i] - v1[i] * sn[i]) * qs; o1[i] = (v1[i] * cc[i] + v0[i] * sn[i]) * qs; }
;                     bf16_t* dst = (tile < 7 ? QC : KC) + ((size_t)((bl_ * 8 + ((tile - 5) & 1) * 4 + wc) * SEQ + sq_)) * 64 + 8 * fq;
;                     *(u32x4*)(dst) = pack8(o0);
;                     *(u32x4*)(dst + 32) = pack8(o1);
;                 } else if (tile == 23) {
;                     if (wc == 0 && fq == 0) {
;                         float* mo = mif + (size_t)row * 8;
;                         *(v4f*)(mo) = (v4f){v0[0] + gate_b[0], v0[1] + gate_b[1], v0[2] + gate_b[2], v0[3] + gate_b[3]};
;                         *(v4f*)(mo + 4) = (v4f){v0[4] + gate_b[4], v0[5] + gate_b[5], v0[6] + gate_b[6], v0[7] + gate_b[7]};
;                     }
;                 } else if (tile == 9 || tile == 10) {
;                     bf16_t* d0 = VC + ((size_t)(((bl_ * 4 + (tile - 9) * 2 + 0) * 2 + (wc >> 1)) * SEQ + sq_)) * 64 + (wc & 1) * 32 + 8 * fq;
;                     bf16_t* d1 = VC + ((size_t)(((bl_ * 4 + (tile - 9) * 2 + 1) * 2 + (wc >> 1)) * SEQ + sq_)) * 64 + (wc & 1) * 32 + 8 * fq;
;                     *(u32x4*)d0 = pack8(v0); *(u32x4*)d1 = pack8(v1);
.LBB0_1257:
	v_mov_b32_e32 v68, v226
	v_mov_b32_e32 v69, v227
	v_mov_b32_e32 v70, v228
	v_mov_b32_e32 v71, v229
	v_mov_b32_e32 v76, v69
	v_mov_b32_e32 v77, v70
	v_mov_b32_e32 v69, v71
	v_pk_add_f32 v[68:69], v[76:77], v[68:69]
	s_mov_b64 s[6:7], -1
	v_add_f32_e32 v68, v68, v69
	ds_bpermute_b32 v69, v194, v68
	s_waitcnt lgkmcnt(0)
	v_add_f32_e32 v68, v68, v69
	ds_bpermute_b32 v69, v195, v68
	s_waitcnt lgkmcnt(0)
	v_add_f32_e32 v68, v68, v69
	v_fmamk_f32 v68, v68, 0x3a800000, v235
	s_nop 1
	v_rsq_f32_e32 v76, v68
	s_nop 0
	s_nop 0
	v_pk_mul_f32 v[68:69], v[44:45], v[76:77] op_sel_hi:[1,0]
	v_pk_mul_f32 v[70:71], v[36:37], v[76:77] op_sel_hi:[1,0]
	v_pk_mul_f32 v[44:45], v[46:47], v[76:77] op_sel_hi:[1,0]
	v_pk_mul_f32 v[46:47], v[38:39], v[76:77] op_sel_hi:[1,0]
	v_pk_mul_f32 v[36:37], v[40:41], v[76:77] op_sel_hi:[1,0]
	v_pk_mul_f32 v[38:39], v[28:29], v[76:77] op_sel_hi:[1,0]
	v_pk_mul_f32 v[28:29], v[42:43], v[76:77] op_sel_hi:[1,0]
	v_pk_mul_f32 v[30:31], v[30:31], v[76:77] op_sel_hi:[1,0]
	v_and_b32_e32 v42, 0xfef, v74
	s_and_b64 vcc, exec, s[10:11]
	s_cbranch_vccnz .LBB0_1273
	s_and_b64 vcc, exec, s[8:9]
	s_cbranch_vccnz .LBB0_1268
	s_andn2_b64 vcc, exec, s[92:93]
	s_cbranch_vccnz .LBB0_1265
	v_mov_b64_e32 v[40:41], s[12:13]
	v_mad_i64_i32 v[40:41], s[6:7], v74, s29, v[40:41]
	s_andn2_b64 vcc, exec, s[90:91]
	s_mov_b64 s[6:7], -1
	s_cbranch_vccnz .LBB0_1262
	v_lshl_add_u64 v[80:81], s[88:89], 1, v[40:41]
	s_lshl_b32 s30, s68, 1
	v_lshl_add_u64 v[80:81], v[80:81], 0, s[30:31]
	v_mov_b32_e32 v145, v221
	v_cvt_pk_bf16_f32 v76, v68, v69
	v_cvt_pk_bf16_f32 v77, v44, v45
	v_cvt_pk_bf16_f32 v78, v36, v37
	v_cvt_pk_bf16_f32 v79, v28, v29
	v_lshl_add_u64 v[80:81], v[80:81], 0, v[144:145]
	global_store_dwordx4 v[80:81], v[76:79], off
	s_mov_b64 s[6:7], 0
	s_nop 0
	v_cvt_pk_bf16_f32 v76, v70, v71
	v_cvt_pk_bf16_f32 v77, v46, v47
	v_cvt_pk_bf16_f32 v78, v38, v39
	v_cvt_pk_bf16_f32 v79, v30, v31
	global_store_dwordx4 v[80:81], v[76:79], off offset:256

;     __device__ __forceinline__ void operator()(const f32x4 (&acc)[2][2][4][2], const Unit& u, int wr, int wc, int, int) const {
;     ...
;             for (int mm = 0; mm < 2; ++mm) { const int m = (ab & 1) * 2 + mm;
;                 const int row = row0 + ai * HALF + m * 16; const float rs = rstd_from_quarter(pq[mm], fq * 16 + fr);
;                 float v0[8], v1[8];
; #pragma unroll
;                 for (int n = 0; n < 2; ++n)
; #pragma unroll
;                     for (int i = 0; i < 4; ++i) { v0[n * 4 + i] = acc[ai][0][m][n][i] * rs; v1[n * 4 + i] = acc[ai][1][m][n][i] * rs; }
;                 bf16_t* zr = Z + (size_t)row * ZP + (tile < 5 ? tile : 0) * 256;
;                 const int bl_ = row >> 12, sq_ = row & (SEQ - 1);
;                 if (tile >= 5 && tile <= 8) {
;                     const v4f c0 = cs[mm][0], c1 = cs[mm][1], s0 = cs[mm][2], s1 = cs[mm][3];
;                     const float cc[8] = {c0.x, c0.y, c0.z, c0.w, c1.x, c1.y, c1.z, c1.w}, sn[8] = {s0.x, s0.y, s0.z, s0.w, s1.x, s1.y, s1.z, s1.w};
;                     const float qs = tile < 7 ? QC2 : 1.0f;
;                     float o0[8], o1[8];
; #pragma unroll
;                     for (int i = 0; i < 8; ++i) { o0[i] = (v0[i] * cc[i] - v1[i] * sn[i]) * qs; o1[i] = (v1[i] * cc[i] + v0[i] * sn[i]) * qs; }
;                     bf16_t* dst = (tile < 7 ? QC : KC) + ((size_t)((bl_ * 8 + ((tile - 5) & 1) * 4 + wc) * SEQ + sq_)) * 64 + 8 * fq;
;                     *(u32x4*)(dst) = pack8(o0);
;                     *(u32x4*)(dst + 32) = pack8(o1);
;                 } else if (tile == 23) {
;                     if (wc == 0 && fq == 0) {
;                         float* mo = mif + (size_t)row * 8;
;                         *(v4f*)(mo) = (v4f){v0[0] + gate_b[0], v0[1] + gate_b[1], v0[2] + gate_b[2], v0[3] + gate_b[3]};
;                         *(v4f*)(mo + 4) = (v4f){v0[4] + gate_b[4], v0[5] + gate_b[5], v0[6] + gate_b[6], v0[7] + gate_b[7]};
;                     }
;                 } else if (tile == 9 || tile == 10) {
;                     bf16_t* d0 = VC + ((size_t)(((bl_ * 4 + (tile - 9) * 2 + 0) * 2 + (wc >> 1)) * SEQ + sq_)) * 64 + (wc & 1) * 32 + 8 * fq;
;                     bf16_t* d1 = VC + ((size_t)(((bl_ * 4 + (tile - 9) * 2 + 1) * 2 + (wc >> 1)) * SEQ + sq_)) * 64 + (wc & 1) * 32 + 8 * fq;
;                     *(u32x4*)d0 = pack8(v0); *(u32x4*)d1 = pack8(v1);
.LBB0_1275:
	v_mov_b32_e32 v64, v240
	v_mov_b32_e32 v65, v241
	v_mov_b32_e32 v66, v242
	v_mov_b32_e32 v67, v243
	s_nop 0
	v_mov_b32_e32 v28, v65
	v_mov_b32_e32 v29, v66
	v_mov_b32_e32 v65, v67
	v_pk_add_f32 v[28:29], v[28:29], v[64:65]
	v_and_b32_e32 v36, 0xfff, v72
	v_add_f32_e32 v28, v28, v29
	ds_bpermute_b32 v29, v194, v28
	s_mov_b64 s[6:7], -1
	s_waitcnt lgkmcnt(0)
	v_add_f32_e32 v28, v28, v29
	ds_bpermute_b32 v29, v195, v28
	s_waitcnt lgkmcnt(0)
	v_add_f32_e32 v28, v28, v29
	v_fmamk_f32 v28, v28, 0x3a800000, v235
	s_nop 1
	v_rsq_f32_e32 v38, v28
	s_nop 0
	s_nop 0
	v_pk_mul_f32 v[28:29], v[12:13], v[38:39] op_sel_hi:[1,0]
	v_pk_mul_f32 v[30:31], v[4:5], v[38:39] op_sel_hi:[1,0]
	v_pk_mul_f32 v[12:13], v[14:15], v[38:39] op_sel_hi:[1,0]
	v_pk_mul_f32 v[14:15], v[6:7], v[38:39] op_sel_hi:[1,0]
	v_pk_mul_f32 v[4:5], v[8:9], v[38:39] op_sel_hi:[1,0]
	v_pk_mul_f32 v[6:7], v[0:1], v[38:39] op_sel_hi:[1,0]
	v_pk_mul_f32 v[0:1], v[10:11], v[38:39] op_sel_hi:[1,0]
	v_pk_mul_f32 v[2:3], v[2:3], v[38:39] op_sel_hi:[1,0]
	s_and_b64 vcc, exec, s[10:11]
	s_cbranch_vccnz .LBB0_1291
	s_and_b64 vcc, exec, s[8:9]
	s_cbranch_vccnz .LBB0_1286
	s_andn2_b64 vcc, exec, s[92:93]
	s_cbranch_vccnz .LBB0_1283
	v_mov_b64_e32 v[8:9], s[12:13]
	v_mad_i64_i32 v[8:9], s[6:7], v72, s29, v[8:9]
	s_andn2_b64 vcc, exec, s[90:91]
	s_mov_b64 s[6:7], -1
	s_cbranch_vccnz .LBB0_1280
	v_lshl_add_u64 v[10:11], s[88:89], 1, v[8:9]
	s_lshl_b32 s30, s68, 1
	v_lshl_add_u64 v[10:11], v[10:11], 0, s[30:31]
	v_mov_b32_e32 v145, v221
	v_cvt_pk_bf16_f32 v38, v28, v29
	v_cvt_pk_bf16_f32 v39, v12, v13
	v_cvt_pk_bf16_f32 v40, v4, v5
	v_cvt_pk_bf16_f32 v41, v0, v1
	v_lshl_add_u64 v[10:11], v[10:11], 0, v[144:145]
	global_store_dwordx4 v[10:11], v[38:41], off
	s_mov_b64 s[6:7], 0
	s_nop 0
	v_cvt_pk_bf16_f32 v38, v30, v31
	v_cvt_pk_bf16_f32 v39, v14, v15
	v_cvt_pk_bf16_f32 v40, v6, v7
	v_cvt_pk_bf16_f32 v41, v2, v3
	global_store_dwordx4 v[10:11], v[38:41], off offset:256

; __device__ __forceinline__ void unpack8(const v4u r, float* x) { x[0] = bflo(r.x); x[1] = bfhi(r.x); x[2] = bflo(r.y); x[3] = bfhi(r.y); x[4] = bflo(r.z); x[5] = bfhi(r.z); x[6] = bflo(r.w); x[7] = bfhi(r.w); }
; __device__ __forceinline__ float wave_sum(float v, int lane) { return lane63_(wave_incl_sum(v, lane)); }
; __device__ __forceinline__ size_t tl(int row, int col, int K) { return (size_t)(row >> 8) * ((size_t)256 * K) + (size_t)(col >> 6) * (256 * 64) + (size_t)((row & 255) * 64 + (col & 63)); }
; __global__ void __launch_bounds__(NTHR, 2) trunk_fwd(Args args) {
;     ...
;       for (int row0 = gw; row0 < MROWS; row0 += 4 * NGW) {
;         v4u ra[4], rb[4];
; #pragma unroll
;         for (int k = 0; k < 4; ++k) { const int row = row0 + k * NGW < MROWS ? row0 + k * NGW : row0; const u16* xr = xb + tl(row, 16 * lane, DM); ra[k] = *(const v4u*)xr; rb[k] = *(const v4u*)(xr + 8); }
;         asm volatile("" ::: "memory");
; #pragma unroll
;         for (int k = 0; k < 4; ++k) { const int row = row0 + k * NGW; if (row < MROWS) { float x[16]; float sq = 0.f;
;             unpack8(ra[k], x); unpack8(rb[k], x + 8);
; #pragma unroll
;             for (int i = 0; i < 16; ++i) sq += x[i] * x[i];
;             const float rs = rsqrtf(wave_sum(sq, lane) * (1.0f / DM) + EPS);
;             v4f* op = (v4f*)(outp + (size_t)row * DM + 16 * lane);
; #pragma unroll
;             for (int j = 0; j < 4; ++j) op[j] = (v4f){x[4 * j] * rs * gg[j].x, x[4 * j + 1] * rs * gg[j].y, x[4 * j + 2] * rs * gg[j].z, x[4 * j + 3] * rs * gg[j].w}; } }
.LBB0_1417:
	s_waitcnt vmcnt(5)
	v_ashrrev_i32_e32 v16, 8, v44
	v_ashrrev_i32_e32 v17, 31, v16
	v_and_or_b32 v18, v49, s14, v48
	v_lshlrev_b64 v[16:17], 19, v[16:17]
	v_lshl_add_u64 v[16:17], s[6:7], 0, v[16:17]
	v_lshlrev_b32_e32 v40, 1, v18
	v_lshl_add_u64 v[16:17], v[16:17], 0, v[40:41]
	global_load_dwordx4 v[54:57], v[16:17], off
	global_load_dwordx4 v[58:61], v[16:17], off offset:16
	v_add_u32_e32 v46, s26, v44
	v_cmp_gt_i32_e64 s[2:3], s10, v46
	v_add_u32_e32 v18, s26, v46
	v_cmp_gt_i32_e64 s[0:1], s10, v18
	v_cndmask_b32_e64 v17, v44, v46, s[2:3]
	v_add_u32_e32 v52, s26, v18
	v_ashrrev_i32_e32 v16, 8, v17
	v_lshlrev_b32_e32 v19, 6, v17
	s_waitcnt vmcnt(6)
	v_cndmask_b32_e64 v20, v44, v18, s[0:1]
	v_cmp_gt_i32_e32 vcc, s10, v52
	v_ashrrev_i32_e32 v17, 31, v16
	v_and_or_b32 v19, v19, s14, v48
	v_ashrrev_i32_e32 v18, 8, v20
	v_lshlrev_b32_e32 v20, 6, v20
	v_cndmask_b32_e32 v21, v44, v52, vcc
	v_lshlrev_b64 v[16:17], 19, v[16:17]
	v_lshlrev_b32_e32 v40, 1, v19
	v_ashrrev_i32_e32 v19, 31, v18
	v_and_or_b32 v22, v20, s14, v48
	v_ashrrev_i32_e32 v20, 8, v21
	v_lshlrev_b32_e32 v23, 6, v21
	v_lshl_add_u64 v[16:17], s[6:7], 0, v[16:17]
	v_lshlrev_b64 v[18:19], 19, v[18:19]
	v_ashrrev_i32_e32 v21, 31, v20
	v_and_or_b32 v23, v23, s14, v48
	v_lshl_add_u64 v[16:17], v[16:17], 0, v[40:41]
	v_lshl_add_u64 v[18:19], s[6:7], 0, v[18:19]
	v_lshlrev_b32_e32 v40, 1, v22
	v_lshlrev_b64 v[20:21], 19, v[20:21]
	global_load_dwordx4 v[32:35], v[16:17], off offset:16
	global_load_dwordx4 v[36:39], v[16:17], off
	v_lshl_add_u64 v[16:17], v[18:19], 0, v[40:41]
	v_lshl_add_u64 v[18:19], s[6:7], 0, v[20:21]
	v_lshlrev_b32_e32 v40, 1, v23
	v_lshl_add_u64 v[62:63], v[18:19], 0, v[40:41]
	global_load_dwordx4 v[24:27], v[16:17], off offset:16
	global_load_dwordx4 v[28:31], v[16:17], off
	s_nop 0
	global_load_dwordx4 v[16:19], v[62:63], off offset:16
	global_load_dwordx4 v[20:23], v[62:63], off
	v_mov_b32_e32 v47, v41
	v_mov_b32_e32 v40, v41
	v_ashrrev_i32_e32 v45, 31, v44
	s_waitcnt vmcnt(7)
	v_lshlrev_b32_e32 v62, 16, v54
	v_and_b32_e32 v63, 0xffff0000, v54
	v_lshlrev_b32_e32 v54, 16, v55
	v_and_b32_e32 v55, 0xffff0000, v55
	s_waitcnt vmcnt(6)
	v_lshlrev_b32_e32 v68, 16, v60
	v_and_b32_e32 v69, 0xffff0000, v60
	v_lshlrev_b32_e32 v70, 16, v61
	v_and_b32_e32 v71, 0xffff0000, v61
	v_pk_mul_f32 v[60:61], v[62:63], v[62:63]
	v_pk_mul_f32 v[72:73], v[54:55], v[54:55]
	v_add_f32_e32 v53, v60, v61
	v_lshlrev_b32_e32 v64, 16, v56
	v_and_b32_e32 v65, 0xffff0000, v56
	v_add_f32_e32 v53, v53, v72
	v_pk_mul_f32 v[74:75], v[64:65], v[64:65]
	v_add_f32_e32 v53, v53, v73
	v_lshlrev_b32_e32 v56, 16, v57
	v_and_b32_e32 v57, 0xffff0000, v57
	v_add_f32_e32 v53, v53, v74
	v_pk_mul_f32 v[76:77], v[56:57], v[56:57]
	v_add_f32_e32 v53, v53, v75
	v_lshlrev_b32_e32 v66, 16, v58
	v_and_b32_e32 v67, 0xffff0000, v58
	v_add_f32_e32 v53, v53, v76
	v_pk_mul_f32 v[78:79], v[66:67], v[66:67]
	v_add_f32_e32 v53, v53, v77
	v_lshlrev_b32_e32 v58, 16, v59
	v_and_b32_e32 v59, 0xffff0000, v59
	v_add_f32_e32 v53, v53, v78
	v_pk_mul_f32 v[80:81], v[58:59], v[58:59]
	v_add_f32_e32 v53, v53, v79
	v_add_f32_e32 v53, v53, v80
	v_pk_mul_f32 v[82:83], v[68:69], v[68:69]
	v_add_f32_e32 v53, v53, v81
	v_add_f32_e32 v53, v53, v82
	v_pk_mul_f32 v[84:85], v[70:71], v[70:71]
	v_add_f32_e32 v53, v53, v83
	v_add_f32_e32 v53, v53, v84
	v_add_f32_e32 v53, v53, v85
	v_lshlrev_b64 v[60:61], 12, v[44:45]
	v_lshl_add_u64 v[72:73], v[42:43], 0, v[60:61]
	v_add_f32_dpp v53, v53, v53 row_shr:1 row_mask:0xf bank_mask:0xf bound_ctrl:1
	s_nop 1
	v_add_f32_dpp v53, v53, v53 row_shr:2 row_mask:0xf bank_mask:0xf bound_ctrl:1
	s_nop 1
	v_add_f32_dpp v53, v53, v53 row_shr:4 row_mask:0xf bank_mask:0xf bound_ctrl:1
	s_nop 1
	v_add_f32_dpp v53, v53, v53 row_shr:8 row_mask:0xf bank_mask:0xf bound_ctrl:1
	s_nop 1
	v_mov_b32_dpp v47, v53 row_bcast:15 row_mask:0xa bank_mask:0xf
	v_add_f32_e32 v47, v53, v47
	s_nop 1
	v_mov_b32_dpp v40, v47 row_bcast:31 row_mask:0xc bank_mask:0xf
	v_add_f32_e32 v40, v47, v40
	s_nop 0
	v_readlane_b32 s4, v40, 63
	s_nop 1
	v_fma_f32 v40, s4, v51, v50
	s_nop 1
	v_rsq_f32_e32 v40, v40
	s_nop 0
	s_nop 0
	v_pk_mul_f32 v[60:61], v[40:41], v[62:63] op_sel_hi:[0,1]
	v_pk_mul_f32 v[54:55], v[40:41], v[54:55] op_sel_hi:[0,1]
	v_pk_mul_f32 v[62:63], v[40:41], v[64:65] op_sel_hi:[0,1]
	v_pk_mul_f32 v[64:65], v[40:41], v[56:57] op_sel_hi:[0,1]
	v_pk_mul_f32 v[66:67], v[40:41], v[66:67] op_sel_hi:[0,1]
	v_pk_mul_f32 v[74:75], v[40:41], v[58:59] op_sel_hi:[0,1]
	v_pk_mul_f32 v[56:57], v[54:55], v[14:15]
	v_pk_mul_f32 v[54:55], v[60:61], v[12:13]
	v_pk_mul_f32 v[60:61], v[64:65], v[10:11]
	v_pk_mul_f32 v[58:59], v[62:63], v[8:9]
	v_pk_mul_f32 v[64:65], v[74:75], v[6:7]
	v_pk_mul_f32 v[62:63], v[66:67], v[4:5]
	global_store_dwordx4 v[72:73], v[54:57], off
	global_store_dwordx4 v[72:73], v[58:61], off offset:16
	global_store_dwordx4 v[72:73], v[62:65], off offset:32
	v_pk_mul_f32 v[54:55], v[40:41], v[68:69] op_sel_hi:[0,1]
	v_pk_mul_f32 v[56:57], v[40:41], v[70:71] op_sel_hi:[0,1]
	v_pk_mul_f32 v[56:57], v[56:57], v[2:3]
	v_pk_mul_f32 v[54:55], v[54:55], v[0:1]
	global_store_dwordx4 v[72:73], v[54:57], off offset:48
	s_and_saveexec_b64 s[4:5], s[2:3]
	s_cbranch_execnz .LBB0_1420
	s_or_b64 exec, exec, s[4:5]
	s_and_saveexec_b64 s[2:3], s[0:1]
	s_cbranch_execnz .LBB0_1421

; __device__ __forceinline__ void unpack8(const v4u r, float* x) { x[0] = bflo(r.x); x[1] = bfhi(r.x); x[2] = bflo(r.y); x[3] = bfhi(r.y); x[4] = bflo(r.z); x[5] = bfhi(r.z); x[6] = bflo(r.w); x[7] = bfhi(r.w); }
; __device__ __forceinline__ float wave_sum(float v, int lane) { return lane63_(wave_incl_sum(v, lane)); }
; __global__ void __launch_bounds__(NTHR, 2) trunk_fwd(Args args) {
;     ...
;         for (int k = 0; k < 4; ++k) { const int row = row0 + k * NGW; if (row < MROWS) { float x[16]; float sq = 0.f;
;             unpack8(ra[k], x); unpack8(rb[k], x + 8);
; #pragma unroll
;             for (int i = 0; i < 16; ++i) sq += x[i] * x[i];
;             const float rs = rsqrtf(wave_sum(sq, lane) * (1.0f / DM) + EPS);
;             v4f* op = (v4f*)(outp + (size_t)row * DM + 16 * lane);
; #pragma unroll
;             for (int j = 0; j < 4; ++j) op[j] = (v4f){x[4 * j] * rs * gg[j].x, x[4 * j + 1] * rs * gg[j].y, x[4 * j + 2] * rs * gg[j].z, x[4 * j + 3] * rs * gg[j].w}; } }
.LBB0_1420:
	s_waitcnt vmcnt(8)
	v_lshlrev_b32_e32 v54, 16, v36
	v_and_b32_e32 v55, 0xffff0000, v36
	v_pk_mul_f32 v[56:57], v[54:55], v[54:55]
	v_lshlrev_b32_e32 v36, 16, v37
	v_and_b32_e32 v37, 0xffff0000, v37
	v_pk_mul_f32 v[58:59], v[36:37], v[36:37]
	v_add_f32_e32 v40, v56, v57
	v_lshlrev_b32_e32 v60, 16, v38
	v_and_b32_e32 v61, 0xffff0000, v38
	v_add_f32_e32 v40, v40, v58
	v_pk_mul_f32 v[62:63], v[60:61], v[60:61]
	v_add_f32_e32 v40, v40, v59
	v_lshlrev_b32_e32 v38, 16, v39
	v_and_b32_e32 v39, 0xffff0000, v39
	v_add_f32_e32 v40, v40, v62
	v_pk_mul_f32 v[64:65], v[38:39], v[38:39]
	v_add_f32_e32 v40, v40, v63
	v_lshlrev_b32_e32 v66, 16, v32
	v_and_b32_e32 v67, 0xffff0000, v32
	v_add_f32_e32 v40, v40, v64
	v_pk_mul_f32 v[68:69], v[66:67], v[66:67]
	v_add_f32_e32 v40, v40, v65
	v_lshlrev_b32_e32 v70, 16, v33
	v_and_b32_e32 v71, 0xffff0000, v33
	v_add_f32_e32 v40, v40, v68
	v_pk_mul_f32 v[32:33], v[70:71], v[70:71]
	v_add_f32_e32 v40, v40, v69
	v_lshlrev_b32_e32 v72, 16, v34
	v_and_b32_e32 v73, 0xffff0000, v34
	v_add_f32_e32 v32, v40, v32
	v_pk_mul_f32 v[74:75], v[72:73], v[72:73]
	v_add_f32_e32 v32, v32, v33
	v_lshlrev_b32_e32 v76, 16, v35
	v_and_b32_e32 v77, 0xffff0000, v35
	v_add_f32_e32 v32, v32, v74
	v_pk_mul_f32 v[34:35], v[76:77], v[76:77]
	v_add_f32_e32 v32, v32, v75
	v_add_f32_e32 v32, v32, v34
	v_add_f32_e32 v32, v32, v35
	v_mov_b32_e32 v33, v41
	v_ashrrev_i32_e32 v47, 31, v46
	v_add_f32_dpp v32, v32, v32 row_shr:1 row_mask:0xf bank_mask:0xf bound_ctrl:1
	s_nop 1
	v_add_f32_dpp v32, v32, v32 row_shr:2 row_mask:0xf bank_mask:0xf bound_ctrl:1
	s_nop 1
	v_add_f32_dpp v32, v32, v32 row_shr:4 row_mask:0xf bank_mask:0xf bound_ctrl:1
	s_nop 1
	v_add_f32_dpp v32, v32, v32 row_shr:8 row_mask:0xf bank_mask:0xf bound_ctrl:1
	s_nop 1
	v_mov_b32_dpp v33, v32 row_bcast:15 row_mask:0xa bank_mask:0xf
	v_add_f32_e32 v32, v32, v33
	v_mov_b32_e32 v33, v41
	s_nop 1
	v_mov_b32_dpp v33, v32 row_bcast:31 row_mask:0xc bank_mask:0xf
	v_add_f32_e32 v32, v32, v33
	s_nop 0
	v_readlane_b32 s2, v32, 63
	s_nop 1
	v_fma_f32 v32, s2, v51, v50
	s_nop 1
	v_rsq_f32_e32 v40, v32
	v_lshlrev_b64 v[32:33], 12, v[46:47]
	v_lshl_add_u64 v[46:47], v[42:43], 0, v[32:33]
	s_nop 0
	v_pk_mul_f32 v[32:33], v[40:41], v[54:55] op_sel_hi:[0,1]
	v_pk_mul_f32 v[34:35], v[40:41], v[36:37] op_sel_hi:[0,1]
	v_pk_mul_f32 v[34:35], v[34:35], v[14:15]
	v_pk_mul_f32 v[32:33], v[32:33], v[12:13]
	global_store_dwordx4 v[46:47], v[32:35], off
	s_nop 1
	v_pk_mul_f32 v[32:33], v[40:41], v[60:61] op_sel_hi:[0,1]
	v_pk_mul_f32 v[34:35], v[40:41], v[38:39] op_sel_hi:[0,1]
	v_pk_mul_f32 v[34:35], v[34:35], v[10:11]
	v_pk_mul_f32 v[32:33], v[32:33], v[8:9]
	global_store_dwordx4 v[46:47], v[32:35], off offset:16
	s_nop 1
	v_pk_mul_f32 v[32:33], v[40:41], v[66:67] op_sel_hi:[0,1]
	v_pk_mul_f32 v[34:35], v[40:41], v[70:71] op_sel_hi:[0,1]
	v_pk_mul_f32 v[34:35], v[34:35], v[6:7]
	v_pk_mul_f32 v[32:33], v[32:33], v[4:5]
	global_store_dwordx4 v[46:47], v[32:35], off offset:32
	s_nop 1
	v_pk_mul_f32 v[32:33], v[40:41], v[72:73] op_sel_hi:[0,1]
	v_pk_mul_f32 v[34:35], v[40:41], v[76:77] op_sel_hi:[0,1]
	v_pk_mul_f32 v[34:35], v[34:35], v[2:3]
	v_pk_mul_f32 v[32:33], v[32:33], v[0:1]
	global_store_dwordx4 v[46:47], v[32:35], off offset:48
	s_or_b64 exec, exec, s[4:5]
	s_and_saveexec_b64 s[2:3], s[0:1]
	s_cbranch_execz .LBB0_1419
; __device__ __forceinline__ void unpack8(const v4u r, float* x) { x[0] = bflo(r.x); x[1] = bfhi(r.x); x[2] = bflo(r.y); x[3] = bfhi(r.y); x[4] = bflo(r.z); x[5] = bfhi(r.z); x[6] = bflo(r.w); x[7] = bfhi(r.w); }
; __device__ __forceinline__ float wave_sum(float v, int lane) { return lane63_(wave_incl_sum(v, lane)); }
; __global__ void __launch_bounds__(NTHR, 2) trunk_fwd(Args args) {
;     ...
;         for (int k = 0; k < 4; ++k) { const int row = row0 + k * NGW; if (row < MROWS) { float x[16]; float sq = 0.f;
;             unpack8(ra[k], x); unpack8(rb[k], x + 8);
; #pragma unroll
;             for (int i = 0; i < 16; ++i) sq += x[i] * x[i];
;             const float rs = rsqrtf(wave_sum(sq, lane) * (1.0f / DM) + EPS);
;             v4f* op = (v4f*)(outp + (size_t)row * DM + 16 * lane);
; #pragma unroll
;             for (int j = 0; j < 4; ++j) op[j] = (v4f){x[4 * j] * rs * gg[j].x, x[4 * j + 1] * rs * gg[j].y, x[4 * j + 2] * rs * gg[j].z, x[4 * j + 3] * rs * gg[j].w}; } }
.LBB0_1421:
	s_waitcnt vmcnt(6)
	v_lshlrev_b32_e32 v34, 16, v28
	v_and_b32_e32 v35, 0xffff0000, v28
	v_pk_mul_f32 v[36:37], v[34:35], v[34:35]
	v_lshlrev_b32_e32 v28, 16, v29
	v_and_b32_e32 v29, 0xffff0000, v29
	v_pk_mul_f32 v[38:39], v[28:29], v[28:29]
	v_add_f32_e32 v33, v36, v37
	v_lshlrev_b32_e32 v46, 16, v30
	v_and_b32_e32 v47, 0xffff0000, v30
	v_add_f32_e32 v33, v33, v38
	v_pk_mul_f32 v[54:55], v[46:47], v[46:47]
	v_add_f32_e32 v33, v33, v39
	v_lshlrev_b32_e32 v30, 16, v31
	v_and_b32_e32 v31, 0xffff0000, v31
	v_add_f32_e32 v33, v33, v54
	v_pk_mul_f32 v[56:57], v[30:31], v[30:31]
	v_add_f32_e32 v33, v33, v55
	v_lshlrev_b32_e32 v58, 16, v24
	v_and_b32_e32 v59, 0xffff0000, v24
	v_add_f32_e32 v33, v33, v56
	v_pk_mul_f32 v[60:61], v[58:59], v[58:59]
	v_add_f32_e32 v33, v33, v57
	v_lshlrev_b32_e32 v62, 16, v25
	v_and_b32_e32 v63, 0xffff0000, v25
	v_add_f32_e32 v33, v33, v60
	v_pk_mul_f32 v[24:25], v[62:63], v[62:63]
	v_add_f32_e32 v33, v33, v61
	v_lshlrev_b32_e32 v64, 16, v26
	v_and_b32_e32 v65, 0xffff0000, v26
	v_add_f32_e32 v24, v33, v24
	v_pk_mul_f32 v[66:67], v[64:65], v[64:65]
	v_add_f32_e32 v24, v24, v25
	v_lshlrev_b32_e32 v68, 16, v27
	v_and_b32_e32 v69, 0xffff0000, v27
	v_add_f32_e32 v24, v24, v66
	v_pk_mul_f32 v[26:27], v[68:69], v[68:69]
	v_add_f32_e32 v24, v24, v67
	v_add_f32_e32 v24, v24, v26
	v_add_f32_e32 v24, v24, v27
	v_mov_b32_e32 v25, v41
	v_add_u32_e32 v32, s12, v44
	v_add_f32_dpp v24, v24, v24 row_shr:1 row_mask:0xf bank_mask:0xf bound_ctrl:1
	v_ashrrev_i32_e32 v33, 31, v32
	s_nop 0
	v_add_f32_dpp v24, v24, v24 row_shr:2 row_mask:0xf bank_mask:0xf bound_ctrl:1
	s_nop 1
	v_add_f32_dpp v24, v24, v24 row_shr:4 row_mask:0xf bank_mask:0xf bound_ctrl:1
	s_nop 1
	v_add_f32_dpp v24, v24, v24 row_shr:8 row_mask:0xf bank_mask:0xf bound_ctrl:1
	s_nop 1
	v_mov_b32_dpp v25, v24 row_bcast:15 row_mask:0xa bank_mask:0xf
	v_add_f32_e32 v24, v24, v25
	v_mov_b32_e32 v25, v41
	s_nop 1
	v_mov_b32_dpp v25, v24 row_bcast:31 row_mask:0xc bank_mask:0xf
	v_add_f32_e32 v24, v24, v25
	s_nop 0
	v_readlane_b32 s0, v24, 63
	s_nop 1
	v_fma_f32 v24, s0, v51, v50
	s_nop 1
	v_rsq_f32_e32 v36, v24
	v_lshlrev_b64 v[24:25], 12, v[32:33]
	v_lshl_add_u64 v[32:33], v[42:43], 0, v[24:25]
	s_nop 0
	v_pk_mul_f32 v[24:25], v[36:37], v[34:35] op_sel_hi:[0,1]
	v_pk_mul_f32 v[26:27], v[36:37], v[28:29] op_sel_hi:[0,1]
	v_pk_mul_f32 v[26:27], v[26:27], v[14:15]
	v_pk_mul_f32 v[24:25], v[24:25], v[12:13]
	global_store_dwordx4 v[32:33], v[24:27], off
	s_nop 1
	v_pk_mul_f32 v[24:25], v[36:37], v[46:47] op_sel_hi:[0,1]
	v_pk_mul_f32 v[26:27], v[36:37], v[30:31] op_sel_hi:[0,1]
	v_pk_mul_f32 v[26:27], v[26:27], v[10:11]
	v_pk_mul_f32 v[24:25], v[24:25], v[8:9]
	global_store_dwordx4 v[32:33], v[24:27], off offset:16
	s_nop 1
	v_pk_mul_f32 v[24:25], v[36:37], v[58:59] op_sel_hi:[0,1]
	v_pk_mul_f32 v[26:27], v[36:37], v[62:63] op_sel_hi:[0,1]
	v_pk_mul_f32 v[26:27], v[26:27], v[6:7]
	v_pk_mul_f32 v[24:25], v[24:25], v[4:5]
	global_store_dwordx4 v[32:33], v[24:27], off offset:32
	s_nop 1
	v_pk_mul_f32 v[24:25], v[36:37], v[64:65] op_sel_hi:[0,1]
	v_pk_mul_f32 v[26:27], v[36:37], v[68:69] op_sel_hi:[0,1]
	v_pk_mul_f32 v[26:27], v[26:27], v[2:3]
	v_pk_mul_f32 v[24:25], v[24:25], v[0:1]
	global_store_dwordx4 v[32:33], v[24:27], off offset:48
	s_or_b64 exec, exec, s[2:3]
	s_and_saveexec_b64 s[0:1], vcc
	s_cbranch_execz .LBB0_1416
.LBB0_1422:
	s_waitcnt vmcnt(4)
	v_lshlrev_b32_e32 v26, 16, v20
	v_and_b32_e32 v27, 0xffff0000, v20
	v_pk_mul_f32 v[28:29], v[26:27], v[26:27]
	v_lshlrev_b32_e32 v20, 16, v21
	v_and_b32_e32 v21, 0xffff0000, v21
	v_pk_mul_f32 v[30:31], v[20:21], v[20:21]
	v_add_f32_e32 v25, v28, v29
	v_lshlrev_b32_e32 v32, 16, v22
	v_and_b32_e32 v33, 0xffff0000, v22
	v_add_f32_e32 v25, v25, v30
	v_pk_mul_f32 v[34:35], v[32:33], v[32:33]
	v_add_f32_e32 v25, v25, v31
	v_lshlrev_b32_e32 v22, 16, v23
	v_and_b32_e32 v23, 0xffff0000, v23
	v_add_f32_e32 v25, v25, v34
	v_pk_mul_f32 v[36:37], v[22:23], v[22:23]
	v_add_f32_e32 v25, v25, v35
	v_lshlrev_b32_e32 v38, 16, v16
	v_and_b32_e32 v39, 0xffff0000, v16
	v_add_f32_e32 v25, v25, v36
	v_add_u32_e32 v24, s13, v44
	v_pk_mul_f32 v[44:45], v[38:39], v[38:39]
	v_add_f32_e32 v25, v25, v37
	v_lshlrev_b32_e32 v46, 16, v17
	v_and_b32_e32 v47, 0xffff0000, v17
	v_add_f32_e32 v25, v25, v44
	v_pk_mul_f32 v[16:17], v[46:47], v[46:47]
	v_add_f32_e32 v25, v25, v45
	v_lshlrev_b32_e32 v54, 16, v18
	v_and_b32_e32 v55, 0xffff0000, v18
	v_add_f32_e32 v16, v25, v16
	v_pk_mul_f32 v[56:57], v[54:55], v[54:55]
	v_add_f32_e32 v16, v16, v17
	v_lshlrev_b32_e32 v58, 16, v19
	v_and_b32_e32 v59, 0xffff0000, v19
	v_add_f32_e32 v16, v16, v56
	v_pk_mul_f32 v[18:19], v[58:59], v[58:59]
	v_add_f32_e32 v16, v16, v57
	v_add_f32_e32 v16, v16, v18
	v_add_f32_e32 v16, v16, v19
	v_mov_b32_e32 v17, v41
	v_ashrrev_i32_e32 v25, 31, v24
	v_add_f32_dpp v16, v16, v16 row_shr:1 row_mask:0xf bank_mask:0xf bound_ctrl:1
	s_nop 1
	v_add_f32_dpp v16, v16, v16 row_shr:2 row_mask:0xf bank_mask:0xf bound_ctrl:1
	s_nop 1
	v_add_f32_dpp v16, v16, v16 row_shr:4 row_mask:0xf bank_mask:0xf bound_ctrl:1
	s_nop 1
	v_add_f32_dpp v16, v16, v16 row_shr:8 row_mask:0xf bank_mask:0xf bound_ctrl:1
	s_nop 1
	v_mov_b32_dpp v17, v16 row_bcast:15 row_mask:0xa bank_mask:0xf
	v_add_f32_e32 v16, v16, v17
	v_mov_b32_e32 v17, v41
	s_nop 1
	v_mov_b32_dpp v17, v16 row_bcast:31 row_mask:0xc bank_mask:0xf
	v_add_f32_e32 v16, v16, v17
	s_nop 0
	v_readlane_b32 s2, v16, 63
	s_nop 1
	v_fma_f32 v16, s2, v51, v50
	s_nop 1
	v_rsq_f32_e32 v28, v16
	v_lshlrev_b64 v[16:17], 12, v[24:25]
	v_lshl_add_u64 v[24:25], v[42:43], 0, v[16:17]
	s_nop 0
	v_pk_mul_f32 v[16:17], v[28:29], v[26:27] op_sel_hi:[0,1]
	v_pk_mul_f32 v[18:19], v[28:29], v[20:21] op_sel_hi:[0,1]
	v_pk_mul_f32 v[18:19], v[18:19], v[14:15]
	v_pk_mul_f32 v[16:17], v[16:17], v[12:13]
	global_store_dwordx4 v[24:25], v[16:19], off
	s_nop 1
	v_pk_mul_f32 v[16:17], v[28:29], v[32:33] op_sel_hi:[0,1]
	v_pk_mul_f32 v[18:19], v[28:29], v[22:23] op_sel_hi:[0,1]
	v_pk_mul_f32 v[18:19], v[18:19], v[10:11]
	v_pk_mul_f32 v[16:17], v[16:17], v[8:9]
	global_store_dwordx4 v[24:25], v[16:19], off offset:16
	s_nop 1
	v_pk_mul_f32 v[16:17], v[28:29], v[38:39] op_sel_hi:[0,1]
	v_pk_mul_f32 v[18:19], v[28:29], v[46:47] op_sel_hi:[0,1]
	v_pk_mul_f32 v[18:19], v[18:19], v[6:7]
	v_pk_mul_f32 v[16:17], v[16:17], v[4:5]
	global_store_dwordx4 v[24:25], v[16:19], off offset:32
	s_nop 1
	v_pk_mul_f32 v[16:17], v[28:29], v[54:55] op_sel_hi:[0,1]
	v_pk_mul_f32 v[18:19], v[28:29], v[58:59] op_sel_hi:[0,1]
	v_pk_mul_f32 v[18:19], v[18:19], v[2:3]
	v_pk_mul_f32 v[16:17], v[16:17], v[0:1]
	global_store_dwordx4 v[24:25], v[16:19], off offset:48
	s_branch .LBB0_1416
